# plus P3 sample items: ds_bpermute wave sums replaced by exact permlane-swap / DPP register shuffles
# baseline (speedup 1.0000x reference)
.LBB0_823:
	s_mov_b64 s[90:91], 0xffffffff
	s_mov_b32 s92, 0xffff
	s_mov_b32 s93, 0xffff
	s_add_i32 s4, s71, s86
	s_min_i32 s52, s4, 0x3ff
	v_mov_b32_e32 v97, v1
	s_and_b32 s37, s52, 7
	s_lshl_b32 s87, s37, 7
	v_and_b32_e32 v96, 0x7f, v97
	v_or_b32_e32 v28, s87, v96
	s_ashr_i32 s5, s52, 3
	v_lshlrev_b32_e32 v2, 2, v28
	s_mul_i32 s4, s5, 3
	v_lshl_add_u64 v[6:7], s[26:27], 0, v[2:3]
	v_mad_i64_i32 v[6:7], s[6:7], s4, v78, v[6:7]
	v_add_co_u32_e32 v8, vcc, s66, v6
	v_lshl_add_u64 v[22:23], s[16:17], 0, v[2:3]
	s_nop 0
	v_addc_co_u32_e32 v9, vcc, 0, v7, vcc
	v_add_co_u32_e32 v10, vcc, s67, v6
	s_lshl_b32 s8, s5, 2
	s_nop 0
	v_addc_co_u32_e32 v11, vcc, 0, v7, vcc
	global_load_dword v29, v[6:7], off
	global_load_dword v13, v[8:9], off
	s_nop 0
	global_load_dword v10, v[10:11], off
	v_lshlrev_b32_e32 v6, 1, v28
	v_mov_b32_e32 v7, v3
	v_add_co_u32_e32 v24, vcc, s68, v22
	s_add_i32 s42, s8, 0x2000
	v_lshl_add_u64 v[20:21], s[10:11], 0, v[6:7]
	v_addc_co_u32_e32 v25, vcc, 0, v23, vcc
	v_mad_i64_i32 v[6:7], s[6:7], s42, v78, v[20:21]
	v_add_co_u32_e32 v14, vcc, s69, v22
	global_load_ushort v9, v[6:7], off
	global_load_dword v5, v2, s[16:17]
	s_nop 0
	global_load_dword v6, v[24:25], off offset:-4096
	v_addc_co_u32_e32 v15, vcc, 0, v23, vcc
	v_add_co_u32_e32 v26, vcc, s73, v22
	global_load_dword v7, v[14:15], off offset:-4096
	s_nop 0
	v_addc_co_u32_e32 v27, vcc, 0, v23, vcc
	global_load_dword v8, v[26:27], off offset:-4096
	v_or_b32_e32 v12, 0x400, v28
	v_add_co_u32_e32 v16, vcc, s77, v22
	v_lshlrev_b32_e32 v2, 2, v12
	s_nop 0
	v_addc_co_u32_e32 v17, vcc, 0, v23, vcc
	global_load_dword v11, v[14:15], off
	global_load_dword v74, v[16:17], off
	v_lshl_add_u64 v[14:15], s[26:27], 0, v[2:3]
	v_mad_i64_i32 v[14:15], s[6:7], s4, v78, v[14:15]
	s_mul_i32 s5, s5, 0xc000
	v_add_co_u32_e32 v16, vcc, s66, v14
	s_add_i32 s9, s5, 0x6000000
	s_add_i32 s40, s8, 0x2001
	s_add_i32 s38, s8, 0x2002
	s_add_i32 s15, s5, 0x6006000
	s_add_i32 s36, s8, 0x2003
	s_add_i32 s5, s5, 0x6009000
	v_addc_co_u32_e32 v17, vcc, 0, v15, vcc
	s_mul_hi_i32 s14, s42, 0x3000
	v_add_co_u32_e32 v18, vcc, s67, v14
	s_add_u32 s50, s10, s9
	s_nop 0
	v_addc_co_u32_e32 v19, vcc, 0, v15, vcc
	global_load_dword v38, v[14:15], off
	s_nop 0
	global_load_dword v16, v[16:17], off
	s_nop 0
	global_load_dword v14, v[18:19], off
	s_addc_u32 s51, s11, s14
	v_lshlrev_b32_e32 v17, 1, v12
	global_load_ushort v39, v17, s[50:51]
	global_load_dword v18, v2, s[16:17]
	global_load_dword v19, v[24:25], off
	global_load_dword v12, v[26:27], off
	v_add_co_u32_e32 v24, vcc, s74, v22
	s_mul_i32 s9, s40, 0x3000
	s_nop 0
	v_addc_co_u32_e32 v25, vcc, 0, v23, vcc
	v_add_co_u32_e32 v22, vcc, s76, v22
	s_mul_hi_i32 s8, s40, 0x3000
	s_nop 0
	v_addc_co_u32_e32 v23, vcc, 0, v23, vcc
	global_load_dword v76, v[24:25], off
	global_load_dword v75, v[22:23], off
	v_mad_i64_i32 v[22:23], s[6:7], s40, v78, v[20:21]
	v_mad_i64_i32 v[24:25], s[6:7], s38, v78, v[20:21]
	v_mad_i64_i32 v[20:21], s[6:7], s36, v78, v[20:21]
	global_load_ushort v26, v[22:23], off
	global_load_ushort v15, v[24:25], off
	s_nop 0
	global_load_ushort v21, v[20:21], off
	s_add_u32 s48, s10, s9
	v_or_b32_e32 v23, 0x800, v28
	s_addc_u32 s49, s11, s8
	v_lshlrev_b32_e32 v2, 2, v23
	s_mul_hi_i32 s14, s38, 0x3000
	s_add_u32 s46, s10, s15
	s_addc_u32 s47, s11, s14
	v_lshl_add_u64 v[30:31], s[26:27], 0, v[2:3]
	s_add_u32 s44, s10, s5
	v_mad_i64_i32 v[30:31], s[4:5], s4, v78, v[30:31]
	v_add_co_u32_e32 v32, vcc, s66, v30
	s_mul_hi_i32 s39, s36, 0x3000
	s_nop 0
	v_addc_co_u32_e32 v33, vcc, 0, v31, vcc
	v_add_co_u32_e32 v34, vcc, s67, v30
	global_load_dword v77, v2, s[16:17]
	s_addc_u32 s45, s11, s39
	global_load_ushort v28, v17, s[48:49]
	global_load_ushort v25, v17, s[46:47]
	global_load_ushort v22, v17, s[44:45]
	s_waitcnt vmcnt(22)
	v_lshlrev_b32_e32 v20, 16, v9
	s_waitcnt vmcnt(20)
	v_mul_f32_e32 v24, v13, v6
	v_fmac_f32_e32 v24, v29, v5
	v_addc_co_u32_e32 v35, vcc, 0, v31, vcc
	v_ashrrev_i32_e32 v104, 6, v97
	s_waitcnt vmcnt(19)
	v_fmac_f32_e32 v24, v10, v7
	v_and_b32_e32 v40, 63, v97
	s_waitcnt vmcnt(18)
	v_fmac_f32_e32 v24, v8, v20
	v_mul_f32_e32 v9, 0xbfb8aa3b, v24
	v_exp_f32_e32 v9, v9
	s_nop 0
	v_add_f32_e32 v27, 1.0, v9
	global_load_dword v9, v[30:31], off
	global_load_dword v109, v[32:33], off
	global_load_dword v107, v[34:35], off
	v_lshlrev_b32_e32 v30, 1, v23
	v_mov_b32_e32 v31, v3
	v_lshl_add_u64 v[30:31], s[10:11], 0, v[30:31]
	v_mad_i64_i32 v[32:33], s[4:5], s42, v78, v[30:31]
	v_mad_i64_i32 v[34:35], s[4:5], s40, v78, v[30:31]
	v_mad_i64_i32 v[36:37], s[4:5], s38, v78, v[30:31]
	v_mad_i64_i32 v[30:31], s[4:5], s36, v78, v[30:31]
	global_load_ushort v111, v[32:33], off
	global_load_ushort v110, v[34:35], off
	global_load_ushort v108, v[36:37], off
	global_load_ushort v106, v[30:31], off


	s_waitcnt vmcnt(19)
	v_lshlrev_b32_e32 v23, 16, v39

	s_waitcnt vmcnt(17)
	v_mul_f32_e32 v30, v16, v19
	v_fmac_f32_e32 v30, v38, v18
	v_fmac_f32_e32 v30, v14, v11
	s_waitcnt vmcnt(16)
	v_fmac_f32_e32 v30, v12, v23
	v_mul_f32_e32 v31, 0xbfb8aa3b, v30


	v_exp_f32_e32 v31, v31


	s_nop 0
	v_add_f32_e32 v29, 1.0, v31


	v_rcp_f32_e32 v2, v27
	s_nop 0
	v_mul_f32_e32 v2, v24, v2
	v_cmp_eq_u32_e64 s[4:5], 0, v40


	v_cmp_lt_i32_e32 vcc, v81, v80
	v_rcp_f32_e32 v17, v29
	s_nop 0
	v_mul_f32_e32 v17, v30, v17
	v_mul_f32_e32 v27, v17, v17
	v_cndmask_b32_e32 v24, v79, v81, vcc
	v_lshlrev_b32_e32 v98, 2, v24
	v_mul_f32_e32 v24, v2, v2
	v_mov_b32_e32 v178, v24
	v_mov_b32_e32 v179, v24
	s_nop 1
	v_permlane32_swap_b32_e32 v178, v179
	v_cndmask_b32_e64 v24, v178, v179, s[90:91]
	v_mov_b32_e32 v178, v27
	v_mov_b32_e32 v179, v27
	s_nop 1
	v_permlane32_swap_b32_e32 v178, v179
	v_cndmask_b32_e64 v27, v178, v179, s[90:91]
	v_cmp_lt_i32_e32 vcc, v82, v80
	s_waitcnt lgkmcnt(1)
	v_fmac_f32_e32 v24, v2, v2
	v_cndmask_b32_e32 v29, v79, v82, vcc
	v_lshlrev_b32_e32 v99, 2, v29
	s_waitcnt lgkmcnt(0)
	v_fmac_f32_e32 v27, v17, v17
	v_mov_b32_e32 v178, v24
	v_mov_b32_e32 v179, v24
	s_nop 1
	v_permlane16_swap_b32_e32 v178, v179
	v_cndmask_b32_e64 v29, v178, v179, s[92:93]
	v_mov_b32_e32 v178, v27
	v_mov_b32_e32 v179, v27
	s_nop 1
	v_permlane16_swap_b32_e32 v178, v179
	v_cndmask_b32_e64 v30, v178, v179, s[92:93]
	v_cmp_lt_i32_e32 vcc, v83, v80
	s_waitcnt lgkmcnt(1)
	v_add_f32_e32 v24, v24, v29
	v_cndmask_b32_e32 v31, v79, v83, vcc
	v_lshlrev_b32_e32 v100, 2, v31
	s_waitcnt lgkmcnt(0)
	v_add_f32_e32 v27, v27, v30
	v_mov_b32_dpp v29, v24 row_ror:8 row_mask:0xf bank_mask:0xf
	s_nop 0
	v_mov_b32_dpp v30, v27 row_ror:8 row_mask:0xf bank_mask:0xf
	v_cmp_lt_i32_e32 vcc, v84, v80
	s_waitcnt lgkmcnt(1)
	v_add_f32_e32 v24, v24, v29
	v_cndmask_b32_e32 v31, v79, v84, vcc
	v_lshlrev_b32_e32 v101, 2, v31
	s_waitcnt lgkmcnt(0)
	v_add_f32_e32 v27, v27, v30
	v_mov_b32_dpp v178, v24 row_shr:4 row_mask:0xf bank_mask:0xa
	v_mov_b32_dpp v178, v24 row_shl:4 row_mask:0xf bank_mask:0x5
	v_mov_b32_e32 v29, v178
	v_mov_b32_dpp v178, v27 row_shr:4 row_mask:0xf bank_mask:0xa
	v_mov_b32_dpp v178, v27 row_shl:4 row_mask:0xf bank_mask:0x5
	v_mov_b32_e32 v30, v178
	v_cmp_lt_i32_e32 vcc, v85, v80
	s_waitcnt lgkmcnt(1)
	v_add_f32_e32 v24, v24, v29
	v_cndmask_b32_e32 v31, v79, v85, vcc
	v_lshlrev_b32_e32 v102, 2, v31
	s_waitcnt lgkmcnt(0)
	v_add_f32_e32 v30, v27, v30
	v_mov_b32_dpp v29, v24 quad_perm:[2,3,0,1] row_mask:0xf bank_mask:0xf
	s_nop 0
	v_mov_b32_dpp v31, v30 quad_perm:[2,3,0,1] row_mask:0xf bank_mask:0xf
	v_cmp_lt_i32_e32 vcc, v86, v80
	s_waitcnt lgkmcnt(0)
	v_add_f32_e32 v30, v30, v31
	v_cndmask_b32_e32 v27, v79, v86, vcc
	v_lshlrev_b32_e32 v103, 2, v27
	v_add_f32_e32 v27, v24, v29
	s_nop 1
	v_mov_b32_dpp v29, v27 quad_perm:[1,0,3,2] row_mask:0xf bank_mask:0xf
	v_mov_b32_dpp v31, v30 quad_perm:[1,0,3,2] row_mask:0xf bank_mask:0xf
	v_lshlrev_b32_e32 v24, 3, v104
	v_lshl_add_u32 v24, v24, 2, s70
	s_and_saveexec_b64 s[6:7], s[4:5]
	s_cbranch_execz .LBB0_825
	s_waitcnt lgkmcnt(1)
	v_add_f32_e32 v27, v27, v29
	s_waitcnt lgkmcnt(0)
	v_add_f32_e32 v29, v30, v31
	v_add_u32_e32 v30, 0x1000, v24
	ds_write2_b32 v30, v27, v29 offset1:4
.LBB0_825:
	s_or_b64 exec, exec, s[6:7]
	s_waitcnt lgkmcnt(1)
	v_mul_f32_e32 v29, v10, v6
	v_fmac_f32_e32 v29, v13, v5
	s_waitcnt vmcnt(13)
	v_lshlrev_b32_e32 v27, 16, v26
	v_fmac_f32_e32 v29, v7, v20
	v_fmac_f32_e32 v29, v8, v27
	v_mul_f32_e32 v13, 0xbfb8aa3b, v29
	v_exp_f32_e32 v13, v13
	s_waitcnt vmcnt(9)
	v_lshlrev_b32_e32 v26, 16, v28
	s_waitcnt lgkmcnt(0)
	v_mul_f32_e32 v31, v14, v19
	v_fmac_f32_e32 v31, v16, v18
	v_add_f32_e32 v13, 1.0, v13


	v_fmac_f32_e32 v31, v11, v23
	v_fmac_f32_e32 v31, v12, v26
	v_mul_f32_e32 v16, 0xbfb8aa3b, v31

	v_exp_f32_e32 v16, v16


	s_nop 0
	v_add_f32_e32 v16, 1.0, v16


	v_rcp_f32_e32 v28, v13
	s_nop 0
	v_mul_f32_e32 v13, v29, v28


	v_rcp_f32_e32 v28, v16
	s_nop 0
	v_mul_f32_e32 v16, v31, v28
	v_mul_f32_e32 v28, v13, v13
	v_mul_f32_e32 v29, v16, v16
	v_mov_b32_e32 v178, v28
	v_mov_b32_e32 v179, v28
	s_nop 1
	v_permlane32_swap_b32_e32 v178, v179
	v_cndmask_b32_e64 v28, v178, v179, s[90:91]
	v_mov_b32_e32 v178, v29
	v_mov_b32_e32 v179, v29
	s_nop 1
	v_permlane32_swap_b32_e32 v178, v179
	v_cndmask_b32_e64 v29, v178, v179, s[90:91]
	s_waitcnt lgkmcnt(1)
	v_fmac_f32_e32 v28, v13, v13
	s_waitcnt lgkmcnt(0)
	v_fmac_f32_e32 v29, v16, v16
	v_mov_b32_e32 v178, v28
	v_mov_b32_e32 v179, v28
	s_nop 1
	v_permlane16_swap_b32_e32 v178, v179
	v_cndmask_b32_e64 v30, v178, v179, s[92:93]
	v_mov_b32_e32 v178, v29
	v_mov_b32_e32 v179, v29
	s_nop 1
	v_permlane16_swap_b32_e32 v178, v179
	v_cndmask_b32_e64 v31, v178, v179, s[92:93]
	s_waitcnt lgkmcnt(1)
	v_add_f32_e32 v28, v28, v30
	s_waitcnt lgkmcnt(0)
	v_add_f32_e32 v29, v29, v31
	v_mov_b32_dpp v30, v28 row_ror:8 row_mask:0xf bank_mask:0xf
	s_nop 0
	v_mov_b32_dpp v31, v29 row_ror:8 row_mask:0xf bank_mask:0xf
	s_waitcnt lgkmcnt(1)
	v_add_f32_e32 v28, v28, v30
	s_waitcnt lgkmcnt(0)
	v_add_f32_e32 v29, v29, v31
	v_mov_b32_dpp v178, v28 row_shr:4 row_mask:0xf bank_mask:0xa
	v_mov_b32_dpp v178, v28 row_shl:4 row_mask:0xf bank_mask:0x5
	v_mov_b32_e32 v30, v178
	v_mov_b32_dpp v178, v29 row_shr:4 row_mask:0xf bank_mask:0xa
	v_mov_b32_dpp v178, v29 row_shl:4 row_mask:0xf bank_mask:0x5
	v_mov_b32_e32 v31, v178
	s_waitcnt lgkmcnt(1)
	v_add_f32_e32 v28, v28, v30
	s_waitcnt lgkmcnt(0)
	v_add_f32_e32 v31, v29, v31
	v_mov_b32_dpp v30, v28 quad_perm:[2,3,0,1] row_mask:0xf bank_mask:0xf
	s_nop 0
	v_mov_b32_dpp v32, v31 quad_perm:[2,3,0,1] row_mask:0xf bank_mask:0xf
	s_waitcnt lgkmcnt(1)
	v_add_f32_e32 v28, v28, v30
	s_waitcnt lgkmcnt(0)
	v_add_f32_e32 v30, v31, v32
	v_mov_b32_dpp v29, v28 quad_perm:[1,0,3,2] row_mask:0xf bank_mask:0xf
	s_nop 0
	v_mov_b32_dpp v31, v30 quad_perm:[1,0,3,2] row_mask:0xf bank_mask:0xf
	s_and_saveexec_b64 s[6:7], s[4:5]
	s_cbranch_execz .LBB0_827
	s_waitcnt lgkmcnt(1)
	v_add_f32_e32 v28, v28, v29
	s_waitcnt lgkmcnt(0)
	v_add_f32_e32 v29, v30, v31
	v_add_u32_e32 v30, 0x1000, v24
	ds_write2_b32 v30, v28, v29 offset0:1 offset1:5
.LBB0_827:
	s_or_b64 exec, exec, s[6:7]
	v_lshlrev_b32_e32 v28, 16, v15
	v_mul_f32_e32 v15, v6, v20
	v_fmac_f32_e32 v15, v10, v5
	v_fmac_f32_e32 v15, v7, v27
	v_fmac_f32_e32 v15, v8, v28
	v_mul_f32_e32 v10, 0xbfb8aa3b, v15
	s_waitcnt lgkmcnt(1)
	v_exp_f32_e32 v29, v10
	s_waitcnt vmcnt(8)
	v_lshlrev_b32_e32 v10, 16, v25
	s_waitcnt lgkmcnt(0)
	v_mul_f32_e32 v31, v19, v23
	v_fmac_f32_e32 v31, v14, v18
	v_add_f32_e32 v25, 1.0, v29


	v_fmac_f32_e32 v31, v11, v26
	v_fmac_f32_e32 v31, v12, v10
	v_mul_f32_e32 v14, 0xbfb8aa3b, v31


	v_exp_f32_e32 v14, v14


	s_nop 0
	v_add_f32_e32 v32, 1.0, v14


	v_rcp_f32_e32 v14, v25
	s_nop 0
	v_mul_f32_e32 v14, v15, v14


	v_rcp_f32_e32 v15, v32
	s_nop 0
	v_mul_f32_e32 v15, v31, v15
	v_mul_f32_e32 v25, v14, v14
	v_mul_f32_e32 v29, v15, v15
	v_mov_b32_e32 v178, v25
	v_mov_b32_e32 v179, v25
	s_nop 1
	v_permlane32_swap_b32_e32 v178, v179
	v_cndmask_b32_e64 v25, v178, v179, s[90:91]
	v_mov_b32_e32 v178, v29
	v_mov_b32_e32 v179, v29
	s_nop 1
	v_permlane32_swap_b32_e32 v178, v179
	v_cndmask_b32_e64 v29, v178, v179, s[90:91]
	s_waitcnt lgkmcnt(1)
	v_fmac_f32_e32 v25, v14, v14
	s_waitcnt lgkmcnt(0)
	v_fmac_f32_e32 v29, v15, v15
	v_mov_b32_e32 v178, v25
	v_mov_b32_e32 v179, v25
	s_nop 1
	v_permlane16_swap_b32_e32 v178, v179
	v_cndmask_b32_e64 v30, v178, v179, s[92:93]
	v_mov_b32_e32 v178, v29
	v_mov_b32_e32 v179, v29
	s_nop 1
	v_permlane16_swap_b32_e32 v178, v179
	v_cndmask_b32_e64 v31, v178, v179, s[92:93]
	s_waitcnt lgkmcnt(1)
	v_add_f32_e32 v25, v25, v30
	s_waitcnt lgkmcnt(0)
	v_add_f32_e32 v29, v29, v31
	v_mov_b32_dpp v30, v25 row_ror:8 row_mask:0xf bank_mask:0xf
	s_nop 0
	v_mov_b32_dpp v31, v29 row_ror:8 row_mask:0xf bank_mask:0xf
	s_waitcnt lgkmcnt(1)
	v_add_f32_e32 v25, v25, v30
	s_waitcnt lgkmcnt(0)
	v_add_f32_e32 v29, v29, v31
	v_mov_b32_dpp v178, v25 row_shr:4 row_mask:0xf bank_mask:0xa
	v_mov_b32_dpp v178, v25 row_shl:4 row_mask:0xf bank_mask:0x5
	v_mov_b32_e32 v30, v178
	v_mov_b32_dpp v178, v29 row_shr:4 row_mask:0xf bank_mask:0xa
	v_mov_b32_dpp v178, v29 row_shl:4 row_mask:0xf bank_mask:0x5
	v_mov_b32_e32 v31, v178
	s_waitcnt lgkmcnt(1)
	v_add_f32_e32 v25, v25, v30
	s_waitcnt lgkmcnt(0)
	v_add_f32_e32 v31, v29, v31
	v_mov_b32_dpp v30, v25 quad_perm:[2,3,0,1] row_mask:0xf bank_mask:0xf
	s_nop 0
	v_mov_b32_dpp v32, v31 quad_perm:[2,3,0,1] row_mask:0xf bank_mask:0xf
	s_waitcnt lgkmcnt(1)
	v_add_f32_e32 v25, v25, v30
	s_waitcnt lgkmcnt(0)
	v_add_f32_e32 v30, v31, v32
	v_mov_b32_dpp v29, v25 quad_perm:[1,0,3,2] row_mask:0xf bank_mask:0xf
	s_nop 0
	v_mov_b32_dpp v31, v30 quad_perm:[1,0,3,2] row_mask:0xf bank_mask:0xf
	s_and_saveexec_b64 s[6:7], s[4:5]
	s_cbranch_execz .LBB0_829
	s_waitcnt lgkmcnt(1)
	v_add_f32_e32 v25, v25, v29
	s_waitcnt lgkmcnt(0)
	v_add_f32_e32 v29, v30, v31
	v_add_u32_e32 v30, 0x1000, v24
	ds_write2_b32 v30, v25, v29 offset0:2 offset1:6
.LBB0_829:
	s_or_b64 exec, exec, s[6:7]
	v_mul_f32_e32 v6, v6, v27
	v_fmac_f32_e32 v6, v5, v20
	v_lshlrev_b32_e32 v21, 16, v21
	v_fmac_f32_e32 v6, v7, v28
	v_fmac_f32_e32 v6, v8, v21
	v_mul_f32_e32 v5, 0xbfb8aa3b, v6
	v_exp_f32_e32 v5, v5
	v_mul_f32_e32 v19, v19, v26
	v_fmac_f32_e32 v19, v18, v23
	s_waitcnt vmcnt(7)
	v_lshlrev_b32_e32 v7, 16, v22
	v_add_f32_e32 v5, 1.0, v5


	v_fmac_f32_e32 v19, v11, v10
	v_fmac_f32_e32 v19, v12, v7
	v_mul_f32_e32 v7, 0xbfb8aa3b, v19
	v_exp_f32_e32 v7, v7


	s_nop 0
	v_add_f32_e32 v7, 1.0, v7


	v_rcp_f32_e32 v8, v5
	s_nop 0
	v_mul_f32_e32 v11, v6, v8


	v_rcp_f32_e32 v5, v7
	s_nop 0
	v_mul_f32_e32 v12, v19, v5
	v_mul_f32_e32 v5, v11, v11
	v_mul_f32_e32 v6, v12, v12
	v_mov_b32_e32 v178, v5
	v_mov_b32_e32 v179, v5
	s_nop 1
	v_permlane32_swap_b32_e32 v178, v179
	v_cndmask_b32_e64 v5, v178, v179, s[90:91]
	v_mov_b32_e32 v178, v6
	v_mov_b32_e32 v179, v6
	s_nop 1
	v_permlane32_swap_b32_e32 v178, v179
	v_cndmask_b32_e64 v6, v178, v179, s[90:91]
	s_waitcnt lgkmcnt(1)
	v_fmac_f32_e32 v5, v11, v11
	s_waitcnt lgkmcnt(0)
	v_fmac_f32_e32 v6, v12, v12
	v_mov_b32_e32 v178, v5
	v_mov_b32_e32 v179, v5
	s_nop 1
	v_permlane16_swap_b32_e32 v178, v179
	v_cndmask_b32_e64 v7, v178, v179, s[92:93]
	v_mov_b32_e32 v178, v6
	v_mov_b32_e32 v179, v6
	s_nop 1
	v_permlane16_swap_b32_e32 v178, v179
	v_cndmask_b32_e64 v8, v178, v179, s[92:93]
	s_waitcnt lgkmcnt(1)
	v_add_f32_e32 v5, v5, v7
	s_waitcnt lgkmcnt(0)
	v_add_f32_e32 v6, v6, v8
	v_mov_b32_dpp v7, v5 row_ror:8 row_mask:0xf bank_mask:0xf
	s_nop 0
	v_mov_b32_dpp v8, v6 row_ror:8 row_mask:0xf bank_mask:0xf
	s_waitcnt lgkmcnt(1)
	v_add_f32_e32 v5, v5, v7
	s_waitcnt lgkmcnt(0)
	v_add_f32_e32 v6, v6, v8
	v_mov_b32_dpp v178, v5 row_shr:4 row_mask:0xf bank_mask:0xa
	v_mov_b32_dpp v178, v5 row_shl:4 row_mask:0xf bank_mask:0x5
	v_mov_b32_e32 v7, v178
	v_mov_b32_dpp v178, v6 row_shr:4 row_mask:0xf bank_mask:0xa
	v_mov_b32_dpp v178, v6 row_shl:4 row_mask:0xf bank_mask:0x5
	v_mov_b32_e32 v8, v178
	s_waitcnt lgkmcnt(1)
	v_add_f32_e32 v5, v5, v7
	s_waitcnt lgkmcnt(0)
	v_add_f32_e32 v8, v6, v8
	v_mov_b32_dpp v7, v5 quad_perm:[2,3,0,1] row_mask:0xf bank_mask:0xf
	s_nop 0
	v_mov_b32_dpp v10, v8 quad_perm:[2,3,0,1] row_mask:0xf bank_mask:0xf
	s_waitcnt lgkmcnt(1)
	v_add_f32_e32 v5, v5, v7
	s_waitcnt lgkmcnt(0)
	v_add_f32_e32 v7, v8, v10
	v_mov_b32_dpp v6, v5 quad_perm:[1,0,3,2] row_mask:0xf bank_mask:0xf
	s_nop 0
	v_mov_b32_dpp v8, v7 quad_perm:[1,0,3,2] row_mask:0xf bank_mask:0xf
	s_and_saveexec_b64 s[6:7], s[4:5]
	s_cbranch_execz .LBB0_831
	s_waitcnt lgkmcnt(1)
	v_add_f32_e32 v5, v5, v6
	s_waitcnt lgkmcnt(0)
	v_add_f32_e32 v6, v7, v8
	v_add_u32_e32 v7, 0x1000, v24
	ds_write2_b32 v7, v5, v6 offset0:3 offset1:7

.LBB0_848:
	v_add_f32_e32 v2, 0, v2
	v_add_f32_e32 v2, v2, v6
	v_add_f32_e32 v2, v2, v7
	v_add_f32_e32 v2, v2, v8
	v_mul_f32_e32 v2, 0xbfb8aa3b, v2
	v_exp_f32_e32 v2, v2
	v_ashrrev_i32_e32 v154, 7, v97
	v_lshlrev_b32_e32 v6, 6, v154
	v_mul_f32_e32 v5, v10, v13
	v_add_f32_e32 v132, 1.0, v2


	s_ashr_i32 s53, s52, 31
	v_ashrrev_i32_e32 v7, 31, v6
	v_mul_f32_e32 v2, 0x3fb8aa3b, v5
	s_lshl_b64 s[8:9], s[52:53], 14
	v_lshlrev_b64 v[6:7], 7, v[6:7]
	v_exp_f32_e32 v8, v2

	v_lshl_add_u64 v[6:7], v[6:7], 0, s[8:9]

	v_lshl_add_u64 v[10:11], v[6:7], 2, s[24:25]
	v_lshlrev_b32_e32 v2, 2, v96
	v_lshl_add_u64 v[66:67], v[10:11], 0, v[2:3]
	v_add_co_u32_e32 v28, vcc, s85, v66
	global_load_dword v10, v[66:67], off nt
	global_load_dword v11, v[66:67], off offset:512 nt
	global_load_dword v12, v[66:67], off offset:1024 nt
	global_load_dword v13, v[66:67], off offset:1536 nt
	global_load_dword v14, v[66:67], off offset:2048 nt
	global_load_dword v15, v[66:67], off offset:2560 nt
	global_load_dword v16, v[66:67], off offset:3072 nt
	global_load_dword v17, v[66:67], off offset:3584 nt
	v_addc_co_u32_e32 v29, vcc, 0, v67, vcc
	v_add_co_u32_e32 v36, vcc, s65, v66
	v_mul_f32_e32 v155, v109, v76
	s_nop 0
	v_addc_co_u32_e32 v37, vcc, 0, v67, vcc
	global_load_dword v18, v[36:37], off offset:-4096 nt
	global_load_dword v26, v[36:37], off nt
	global_load_dword v27, v[36:37], off offset:512 nt
	v_add_co_u32_e32 v52, vcc, s66, v66
	v_fmac_f32_e32 v155, v9, v77
	s_nop 0
	v_addc_co_u32_e32 v53, vcc, 0, v67, vcc
	v_add_co_u32_e32 v38, vcc, s68, v66
	v_fmac_f32_e32 v155, v107, v75
	s_nop 0
	v_addc_co_u32_e32 v39, vcc, 0, v67, vcc
	global_load_dword v19, v[28:29], off offset:512 nt
	global_load_dword v20, v[28:29], off offset:1024 nt
	global_load_dword v21, v[28:29], off offset:1536 nt
	global_load_dword v22, v[28:29], off offset:2048 nt
	global_load_dword v23, v[28:29], off offset:2560 nt
	global_load_dword v24, v[28:29], off offset:3072 nt
	global_load_dword v25, v[28:29], off offset:3584 nt
	global_load_dword v35, v[52:53], off offset:512 nt
	s_nop 0
	global_load_dword v28, v[36:37], off offset:1024 nt
	global_load_dword v29, v[36:37], off offset:1536 nt
	global_load_dword v30, v[36:37], off offset:2048 nt
	global_load_dword v31, v[36:37], off offset:2560 nt
	global_load_dword v32, v[36:37], off offset:3072 nt
	global_load_dword v33, v[36:37], off offset:3584 nt
	global_load_dword v34, v[38:39], off offset:-4096 nt
	global_load_dword v42, v[38:39], off nt
	v_add_co_u32_e32 v58, vcc, s74, v66
	s_nop 1
	v_addc_co_u32_e32 v59, vcc, 0, v67, vcc
	v_add_co_u32_e32 v68, vcc, s67, v66
	s_nop 1
	v_addc_co_u32_e32 v69, vcc, 0, v67, vcc
	global_load_dword v43, v[38:39], off offset:512 nt
	global_load_dword v44, v[38:39], off offset:1024 nt
	global_load_dword v45, v[38:39], off offset:1536 nt
	global_load_dword v46, v[38:39], off offset:2048 nt
	global_load_dword v47, v[38:39], off offset:2560 nt
	global_load_dword v48, v[38:39], off offset:3072 nt
	global_load_dword v49, v[38:39], off offset:3584 nt
	global_load_dword v50, v[68:69], off offset:-4096 nt
	global_load_dword v36, v[52:53], off offset:1024 nt
	global_load_dword v37, v[52:53], off offset:1536 nt
	s_nop 0
	global_load_dword v38, v[52:53], off offset:2048 nt
	global_load_dword v39, v[52:53], off offset:2560 nt
	global_load_dword v40, v[52:53], off offset:3072 nt
	global_load_dword v41, v[52:53], off offset:3584 nt
	global_load_dword v51, v[58:59], off offset:512 nt
	s_nop 0
	global_load_dword v52, v[58:59], off offset:1024 nt
	global_load_dword v53, v[58:59], off offset:1536 nt
	global_load_dword v54, v[58:59], off offset:2048 nt
	global_load_dword v55, v[58:59], off offset:2560 nt
	global_load_dword v56, v[58:59], off offset:3072 nt
	global_load_dword v57, v[58:59], off offset:3584 nt
	s_nop 0
	global_load_dword v58, v[68:69], off nt
	global_load_dword v59, v[68:69], off offset:512 nt
	global_load_dword v60, v[68:69], off offset:1024 nt
	global_load_dword v61, v[68:69], off offset:1536 nt
	global_load_dword v62, v[68:69], off offset:2048 nt
	global_load_dword v63, v[68:69], off offset:2560 nt
	global_load_dword v64, v[68:69], off offset:3072 nt
	global_load_dword v65, v[68:69], off offset:3584 nt
	v_add_co_u32_e32 v130, vcc, s69, v66
	s_nop 1
	v_addc_co_u32_e32 v131, vcc, 0, v67, vcc
	global_load_dword v66, v[130:131], off nt
	global_load_dword v67, v[130:131], off offset:512 nt
	global_load_dword v68, v[130:131], off offset:1024 nt
	global_load_dword v69, v[130:131], off offset:1536 nt
	global_load_dword v70, v[130:131], off offset:2048 nt
	global_load_dword v71, v[130:131], off offset:2560 nt
	global_load_dword v72, v[130:131], off offset:3072 nt
	global_load_dword v73, v[130:131], off offset:3584 nt
	v_lshlrev_b32_e32 v130, 16, v111
	v_fmac_f32_e32 v155, v74, v130
	v_mul_f32_e32 v9, 0xbfb8aa3b, v155
	v_exp_f32_e32 v9, v9


	s_nop 0
	v_add_f32_e32 v9, 1.0, v9


	v_lshl_add_u32 v111, v154, 8, s70
	v_rcp_f32_e32 v5, v132
	s_nop 0
	v_mul_f32_e32 v5, 1.0, v5
	s_waitcnt lgkmcnt(0)
	s_barrier
	ds_read_b128 v[132:135], v111
	ds_read_b128 v[142:145], v111 offset:16
	ds_read_b128 v[146:149], v111 offset:32
	ds_read_b128 v[150:153], v111 offset:48

	v_cmp_eq_u32_e64 s[8:9], 1, v154
	s_waitcnt vmcnt(62) lgkmcnt(3)
	v_pk_fma_f32 v[132:133], v[10:11], v[132:133], 0 op_sel_hi:[1,1,0]
	s_waitcnt vmcnt(60)
	v_pk_fma_f32 v[132:133], v[12:13], v[134:135], v[132:133]
	s_waitcnt vmcnt(58) lgkmcnt(2)
	v_pk_fma_f32 v[132:133], v[14:15], v[142:143], v[132:133]
	s_waitcnt vmcnt(56)
	v_pk_fma_f32 v[132:133], v[16:17], v[144:145], v[132:133]
	ds_read_b128 v[142:145], v111 offset:80
	s_waitcnt vmcnt(52) lgkmcnt(2)
	v_pk_fma_f32 v[136:137], v[18:19], v[146:147], v[132:133]
	ds_read_b128 v[132:135], v111 offset:64
	s_waitcnt vmcnt(50)
	v_pk_fma_f32 v[136:137], v[20:21], v[148:149], v[136:137]
	ds_read_b128 v[146:149], v111 offset:96
	s_waitcnt vmcnt(48) lgkmcnt(3)
	v_pk_fma_f32 v[136:137], v[22:23], v[150:151], v[136:137]
	s_waitcnt vmcnt(46)
	v_pk_fma_f32 v[136:137], v[24:25], v[152:153], v[136:137]
	s_waitcnt lgkmcnt(1)
	v_pk_fma_f32 v[132:133], v[26:27], v[132:133], v[136:137]
	s_waitcnt vmcnt(43)
	v_pk_fma_f32 v[132:133], v[28:29], v[134:135], v[132:133]
	s_waitcnt vmcnt(41)
	v_pk_fma_f32 v[136:137], v[30:31], v[142:143], v[132:133]
	ds_read_b128 v[132:135], v111 offset:112
	s_waitcnt vmcnt(39)
	v_pk_fma_f32 v[136:137], v[32:33], v[144:145], v[136:137]
	ds_read_b128 v[142:145], v111 offset:128
	s_waitcnt vmcnt(38) lgkmcnt(2)
	v_pk_fma_f32 v[136:137], v[34:35], v[146:147], v[136:137]
	s_waitcnt vmcnt(27)
	v_pk_fma_f32 v[136:137], v[36:37], v[148:149], v[136:137]
	ds_read_b128 v[146:149], v111 offset:144
	s_waitcnt vmcnt(25) lgkmcnt(2)
	v_pk_fma_f32 v[132:133], v[38:39], v[132:133], v[136:137]
	s_waitcnt vmcnt(23)
	v_pk_fma_f32 v[132:133], v[40:41], v[134:135], v[132:133]
	s_waitcnt lgkmcnt(1)
	v_pk_fma_f32 v[136:137], v[42:43], v[142:143], v[132:133]
	ds_read_b128 v[132:135], v111 offset:160
	v_pk_fma_f32 v[136:137], v[44:45], v[144:145], v[136:137]
	ds_read_b128 v[142:145], v111 offset:176
	s_waitcnt lgkmcnt(2)
	v_pk_fma_f32 v[136:137], v[46:47], v[146:147], v[136:137]
	s_nop 0
	v_pk_fma_f32 v[136:137], v[48:49], v[148:149], v[136:137]
	ds_read_b128 v[146:149], v111 offset:192
	s_waitcnt vmcnt(22) lgkmcnt(2)
	v_pk_fma_f32 v[132:133], v[50:51], v[132:133], v[136:137]
	s_waitcnt vmcnt(20)
	v_pk_fma_f32 v[132:133], v[52:53], v[134:135], v[132:133]
	s_waitcnt vmcnt(18) lgkmcnt(1)
	v_pk_fma_f32 v[132:133], v[54:55], v[142:143], v[132:133]
	s_waitcnt vmcnt(16)
	v_pk_fma_f32 v[136:137], v[56:57], v[144:145], v[132:133]
	ds_read_b128 v[132:135], v111 offset:208
	ds_read_b128 v[142:145], v111 offset:224
	s_waitcnt vmcnt(14) lgkmcnt(2)
	v_pk_fma_f32 v[136:137], v[58:59], v[146:147], v[136:137]
	s_waitcnt vmcnt(12)
	v_pk_fma_f32 v[136:137], v[60:61], v[148:149], v[136:137]
	ds_read_b128 v[146:149], v111 offset:240
	s_waitcnt vmcnt(10) lgkmcnt(2)
	v_pk_fma_f32 v[132:133], v[62:63], v[132:133], v[136:137]
	s_waitcnt vmcnt(8)
	v_pk_fma_f32 v[132:133], v[64:65], v[134:135], v[132:133]

	s_waitcnt vmcnt(6) lgkmcnt(1)
	v_pk_fma_f32 v[132:133], v[66:67], v[142:143], v[132:133]
	v_rcp_f32_e32 v134, v9
	s_nop 0
	v_mul_f32_e32 v9, v155, v134
	s_waitcnt vmcnt(4)
	v_pk_fma_f32 v[132:133], v[68:69], v[144:145], v[132:133]
	s_waitcnt vmcnt(2) lgkmcnt(0)
	v_pk_fma_f32 v[132:133], v[70:71], v[146:147], v[132:133]
	s_waitcnt vmcnt(0)
	v_pk_fma_f32 v[132:133], v[72:73], v[148:149], v[132:133]
	s_nop 0
	v_add_f32_e32 v131, v132, v133
	ds_write_b32 v105, v131 offset:4352
	v_add_u32_e32 v131, s70, v2
	s_waitcnt lgkmcnt(0)
	s_barrier
	ds_read2st64_b32 v[132:133], v131 offset0:17 offset1:19
	s_waitcnt lgkmcnt(0)
	v_add_f32_e32 v132, v132, v133
	v_fma_f32 v9, -v8, v132, v9
	v_mul_f32_e32 v136, v5, v9
	ds_read_b128 v[132:135], v111
	ds_read_b128 v[142:145], v111 offset:16
	ds_read_b128 v[146:149], v111 offset:32
	ds_read_b128 v[150:153], v111 offset:48
	ds_read_b128 v[154:157], v111 offset:2048
	s_waitcnt lgkmcnt(4)
	v_pk_mul_f32 v[132:133], v[132:133], v[136:137] op_sel_hi:[1,0]
	s_waitcnt lgkmcnt(3)
	v_pk_mul_f32 v[142:143], v[142:143], v[136:137] op_sel_hi:[1,0]
	v_pk_fma_f32 v[10:11], v[8:9], v[10:11], v[132:133] op_sel_hi:[0,1,1]
	v_pk_mul_f32 v[132:133], v[134:135], v[136:137] op_sel_hi:[1,0]
	s_waitcnt lgkmcnt(0)
	v_pk_fma_f32 v[154:155], v[154:155], v[10:11], 0 op_sel_hi:[1,1,0]
	v_pk_fma_f32 v[12:13], v[8:9], v[12:13], v[132:133] op_sel_hi:[0,1,1]
	ds_read_b128 v[132:135], v111 offset:2064
	v_pk_fma_f32 v[154:155], v[156:157], v[12:13], v[154:155]
	v_pk_fma_f32 v[14:15], v[8:9], v[14:15], v[142:143] op_sel_hi:[0,1,1]
	v_pk_mul_f32 v[142:143], v[144:145], v[136:137] op_sel_hi:[1,0]
	s_waitcnt lgkmcnt(0)
	v_pk_fma_f32 v[132:133], v[132:133], v[14:15], v[154:155]
	v_pk_fma_f32 v[16:17], v[8:9], v[16:17], v[142:143] op_sel_hi:[0,1,1]
	v_pk_fma_f32 v[154:155], v[134:135], v[16:17], v[132:133]
	ds_read_b128 v[132:135], v111 offset:2080
	v_pk_mul_f32 v[142:143], v[136:137], v[146:147] op_sel_hi:[0,1]
	v_pk_fma_f32 v[18:19], v[8:9], v[18:19], v[142:143] op_sel_hi:[0,1,1]
	v_pk_mul_f32 v[142:143], v[136:137], v[148:149] op_sel_hi:[0,1]
	v_pk_fma_f32 v[20:21], v[8:9], v[20:21], v[142:143] op_sel_hi:[0,1,1]
	ds_read_b128 v[142:145], v111 offset:2096
	s_waitcnt lgkmcnt(1)
	v_pk_fma_f32 v[132:133], v[132:133], v[18:19], v[154:155]
	s_nop 0
	v_pk_fma_f32 v[146:147], v[134:135], v[20:21], v[132:133]
	v_pk_mul_f32 v[132:133], v[136:137], v[150:151] op_sel_hi:[0,1]
	v_pk_fma_f32 v[22:23], v[8:9], v[22:23], v[132:133] op_sel_hi:[0,1,1]
	v_pk_mul_f32 v[132:133], v[136:137], v[152:153] op_sel_hi:[0,1]
	v_pk_fma_f32 v[24:25], v[8:9], v[24:25], v[132:133] op_sel_hi:[0,1,1]
	ds_read_b128 v[132:135], v111 offset:64
	s_waitcnt lgkmcnt(1)
	v_pk_fma_f32 v[142:143], v[142:143], v[22:23], v[146:147]
	s_waitcnt lgkmcnt(0)
	v_pk_mul_f32 v[132:133], v[136:137], v[132:133] op_sel_hi:[0,1]
	v_pk_fma_f32 v[150:151], v[144:145], v[24:25], v[142:143]
	ds_read_b128 v[142:145], v111 offset:2112
	ds_read_b128 v[146:149], v111 offset:80
	v_pk_fma_f32 v[26:27], v[8:9], v[26:27], v[132:133] op_sel_hi:[0,1,1]
	v_pk_mul_f32 v[132:133], v[136:137], v[134:135] op_sel_hi:[0,1]
	v_pk_fma_f32 v[28:29], v[8:9], v[28:29], v[132:133] op_sel_hi:[0,1,1]
	ds_read_b128 v[132:135], v111 offset:2128
	s_waitcnt lgkmcnt(2)
	v_pk_fma_f32 v[142:143], v[142:143], v[26:27], v[150:151]
	s_nop 0
	v_pk_fma_f32 v[150:151], v[144:145], v[28:29], v[142:143]
	s_waitcnt lgkmcnt(1)
	v_pk_mul_f32 v[142:143], v[136:137], v[146:147] op_sel_hi:[0,1]
	v_pk_fma_f32 v[30:31], v[8:9], v[30:31], v[142:143] op_sel_hi:[0,1,1]
	v_pk_mul_f32 v[142:143], v[136:137], v[148:149] op_sel_hi:[0,1]
	v_pk_fma_f32 v[32:33], v[8:9], v[32:33], v[142:143] op_sel_hi:[0,1,1]
	ds_read_b128 v[142:145], v111 offset:96
	s_waitcnt lgkmcnt(1)
	v_pk_fma_f32 v[132:133], v[132:133], v[30:31], v[150:151]
	s_waitcnt lgkmcnt(0)
	v_pk_mul_f32 v[142:143], v[136:137], v[142:143] op_sel_hi:[0,1]
	v_pk_fma_f32 v[150:151], v[134:135], v[32:33], v[132:133]
	ds_read_b128 v[132:135], v111 offset:2144
	ds_read_b128 v[146:149], v111 offset:112
	v_pk_fma_f32 v[34:35], v[8:9], v[34:35], v[142:143] op_sel_hi:[0,1,1]
	v_pk_mul_f32 v[142:143], v[136:137], v[144:145] op_sel_hi:[0,1]
	v_pk_fma_f32 v[36:37], v[8:9], v[36:37], v[142:143] op_sel_hi:[0,1,1]
	ds_read_b128 v[142:145], v111 offset:2160
	s_waitcnt lgkmcnt(2)
	v_pk_fma_f32 v[132:133], v[132:133], v[34:35], v[150:151]
	s_nop 0
	v_pk_fma_f32 v[150:151], v[134:135], v[36:37], v[132:133]
	s_waitcnt lgkmcnt(1)
	v_pk_mul_f32 v[132:133], v[136:137], v[146:147] op_sel_hi:[0,1]
	v_pk_fma_f32 v[38:39], v[8:9], v[38:39], v[132:133] op_sel_hi:[0,1,1]
	v_pk_mul_f32 v[132:133], v[136:137], v[148:149] op_sel_hi:[0,1]
	v_pk_fma_f32 v[40:41], v[8:9], v[40:41], v[132:133] op_sel_hi:[0,1,1]
	ds_read_b128 v[132:135], v111 offset:128
	s_waitcnt lgkmcnt(1)
	v_pk_fma_f32 v[142:143], v[142:143], v[38:39], v[150:151]
	s_waitcnt lgkmcnt(0)
	v_pk_mul_f32 v[132:133], v[136:137], v[132:133] op_sel_hi:[0,1]
	v_pk_fma_f32 v[150:151], v[144:145], v[40:41], v[142:143]
	ds_read_b128 v[142:145], v111 offset:2176
	ds_read_b128 v[146:149], v111 offset:144
	v_pk_fma_f32 v[42:43], v[8:9], v[42:43], v[132:133] op_sel_hi:[0,1,1]
	v_pk_mul_f32 v[132:133], v[136:137], v[134:135] op_sel_hi:[0,1]
	v_pk_fma_f32 v[44:45], v[8:9], v[44:45], v[132:133] op_sel_hi:[0,1,1]
	ds_read_b128 v[132:135], v111 offset:2192
	s_waitcnt lgkmcnt(2)
	v_pk_fma_f32 v[142:143], v[142:143], v[42:43], v[150:151]
	s_nop 0
	v_pk_fma_f32 v[150:151], v[144:145], v[44:45], v[142:143]
	s_waitcnt lgkmcnt(1)
	v_pk_mul_f32 v[142:143], v[136:137], v[146:147] op_sel_hi:[0,1]
	v_pk_fma_f32 v[46:47], v[8:9], v[46:47], v[142:143] op_sel_hi:[0,1,1]
	v_pk_mul_f32 v[142:143], v[136:137], v[148:149] op_sel_hi:[0,1]
	v_pk_fma_f32 v[48:49], v[8:9], v[48:49], v[142:143] op_sel_hi:[0,1,1]
	ds_read_b128 v[142:145], v111 offset:160
	s_waitcnt lgkmcnt(1)
	v_pk_fma_f32 v[132:133], v[132:133], v[46:47], v[150:151]
	s_waitcnt lgkmcnt(0)
	v_pk_mul_f32 v[142:143], v[136:137], v[142:143] op_sel_hi:[0,1]
	v_pk_fma_f32 v[150:151], v[134:135], v[48:49], v[132:133]
	ds_read_b128 v[132:135], v111 offset:2208
	ds_read_b128 v[146:149], v111 offset:176
	v_pk_fma_f32 v[50:51], v[8:9], v[50:51], v[142:143] op_sel_hi:[0,1,1]
	v_pk_mul_f32 v[142:143], v[136:137], v[144:145] op_sel_hi:[0,1]
	v_pk_fma_f32 v[52:53], v[8:9], v[52:53], v[142:143] op_sel_hi:[0,1,1]
	ds_read_b128 v[142:145], v111 offset:2224
	s_waitcnt lgkmcnt(2)
	v_pk_fma_f32 v[132:133], v[132:133], v[50:51], v[150:151]
	s_nop 0
	v_pk_fma_f32 v[150:151], v[134:135], v[52:53], v[132:133]
	s_waitcnt lgkmcnt(1)
	v_pk_mul_f32 v[132:133], v[136:137], v[146:147] op_sel_hi:[0,1]
	v_pk_fma_f32 v[54:55], v[8:9], v[54:55], v[132:133] op_sel_hi:[0,1,1]
	v_pk_mul_f32 v[132:133], v[136:137], v[148:149] op_sel_hi:[0,1]
	v_pk_fma_f32 v[56:57], v[8:9], v[56:57], v[132:133] op_sel_hi:[0,1,1]
	ds_read_b128 v[132:135], v111 offset:192
	s_waitcnt lgkmcnt(1)
	v_pk_fma_f32 v[142:143], v[142:143], v[54:55], v[150:151]
	s_waitcnt lgkmcnt(0)
	v_pk_mul_f32 v[132:133], v[136:137], v[132:133] op_sel_hi:[0,1]
	v_pk_fma_f32 v[150:151], v[144:145], v[56:57], v[142:143]
	ds_read_b128 v[142:145], v111 offset:2240
	ds_read_b128 v[146:149], v111 offset:208
	v_pk_fma_f32 v[58:59], v[8:9], v[58:59], v[132:133] op_sel_hi:[0,1,1]
	v_pk_mul_f32 v[132:133], v[136:137], v[134:135] op_sel_hi:[0,1]
	v_pk_fma_f32 v[60:61], v[8:9], v[60:61], v[132:133] op_sel_hi:[0,1,1]
	s_waitcnt lgkmcnt(1)
	v_pk_fma_f32 v[142:143], v[142:143], v[58:59], v[150:151]
	ds_read_b128 v[132:135], v111 offset:2256
	v_pk_fma_f32 v[150:151], v[144:145], v[60:61], v[142:143]
	s_waitcnt lgkmcnt(1)
	v_pk_mul_f32 v[142:143], v[136:137], v[146:147] op_sel_hi:[0,1]
	v_pk_fma_f32 v[62:63], v[8:9], v[62:63], v[142:143] op_sel_hi:[0,1,1]
	v_pk_mul_f32 v[142:143], v[136:137], v[148:149] op_sel_hi:[0,1]
	v_pk_fma_f32 v[64:65], v[8:9], v[64:65], v[142:143] op_sel_hi:[0,1,1]
	ds_read_b128 v[142:145], v111 offset:224
	s_waitcnt lgkmcnt(1)
	v_pk_fma_f32 v[132:133], v[132:133], v[62:63], v[150:151]
	s_waitcnt lgkmcnt(0)
	v_pk_mul_f32 v[142:143], v[136:137], v[142:143] op_sel_hi:[0,1]
	v_pk_fma_f32 v[150:151], v[134:135], v[64:65], v[132:133]
	ds_read_b128 v[132:135], v111 offset:2272
	ds_read_b128 v[146:149], v111 offset:240
	v_pk_fma_f32 v[66:67], v[8:9], v[66:67], v[142:143] op_sel_hi:[0,1,1]
	v_pk_mul_f32 v[142:143], v[136:137], v[144:145] op_sel_hi:[0,1]
	v_pk_fma_f32 v[68:69], v[8:9], v[68:69], v[142:143] op_sel_hi:[0,1,1]
	ds_read_b128 v[142:145], v111 offset:2288
	s_waitcnt lgkmcnt(2)
	v_pk_fma_f32 v[132:133], v[132:133], v[66:67], v[150:151]
	s_nop 0
	v_pk_fma_f32 v[132:133], v[134:135], v[68:69], v[132:133]
	s_waitcnt lgkmcnt(1)
	v_pk_mul_f32 v[134:135], v[136:137], v[146:147] op_sel_hi:[0,1]
	v_pk_fma_f32 v[70:71], v[8:9], v[70:71], v[134:135] op_sel_hi:[0,1,1]
	v_pk_mul_f32 v[134:135], v[136:137], v[148:149] op_sel_hi:[0,1]
	v_pk_fma_f32 v[8:9], v[8:9], v[72:73], v[134:135] op_sel_hi:[0,1,1]
	s_waitcnt lgkmcnt(0)
	v_pk_fma_f32 v[72:73], v[142:143], v[70:71], v[132:133]
	s_nop 0
	v_pk_fma_f32 v[72:73], v[144:145], v[8:9], v[72:73]
	s_nop 0
	v_add_f32_e32 v5, v72, v73
	s_and_saveexec_b64 s[52:53], s[8:9]
	ds_write_b32 v131, v5 offset:8448
	s_or_b64 exec, exec, s[52:53]
	v_add_f32_e32 v72, 0, v120
	v_add_f32_e32 v72, v72, v121
	v_add_f32_e32 v72, v72, v122
	v_add_f32_e32 v72, v72, v123
	v_mul_f32_e32 v72, 0xbfb8aa3b, v72
	v_exp_f32_e32 v72, v72
	v_mul_f32_e32 v136, v107, v76
	v_fmac_f32_e32 v136, v109, v77
	v_lshlrev_b32_e32 v110, 16, v110
	v_add_f32_e32 v120, 1.0, v72
	v_fmac_f32_e32 v136, v75, v130

	v_fmac_f32_e32 v136, v74, v110

	v_mul_f32_e32 v109, 0xbfb8aa3b, v136
	v_exp_f32_e32 v109, v109
	v_mul_f32_e32 v73, v128, v129
	v_mul_f32_e32 v73, 0x3fb8aa3b, v73

	v_exp_f32_e32 v72, v73


	v_add_f32_e32 v109, 1.0, v109


	v_rcp_f32_e32 v73, v120
	s_nop 0
	v_mul_f32_e32 v73, 1.0, v73


	ds_read_b128 v[120:123], v111 offset:512
	ds_read_b128 v[132:135], v111 offset:528
	ds_read_b128 v[142:145], v111 offset:544
	ds_read_b128 v[146:149], v111 offset:560


	s_waitcnt lgkmcnt(3)
	v_pk_fma_f32 v[120:121], v[10:11], v[120:121], 0 op_sel_hi:[1,1,0]

	v_pk_fma_f32 v[120:121], v[12:13], v[122:123], v[120:121]

	s_waitcnt lgkmcnt(2)
	v_pk_fma_f32 v[120:121], v[14:15], v[132:133], v[120:121]
	s_nop 0
	v_pk_fma_f32 v[120:121], v[16:17], v[134:135], v[120:121]
	ds_read_b128 v[132:135], v111 offset:592
	s_waitcnt lgkmcnt(2)
	v_pk_fma_f32 v[128:129], v[18:19], v[142:143], v[120:121]
	ds_read_b128 v[120:123], v111 offset:576
	v_pk_fma_f32 v[128:129], v[20:21], v[144:145], v[128:129]
	ds_read_b128 v[142:145], v111 offset:608
	s_waitcnt lgkmcnt(3)
	v_pk_fma_f32 v[128:129], v[22:23], v[146:147], v[128:129]
	s_nop 0
	v_pk_fma_f32 v[128:129], v[24:25], v[148:149], v[128:129]
	s_waitcnt lgkmcnt(1)
	v_pk_fma_f32 v[120:121], v[26:27], v[120:121], v[128:129]
	s_nop 0
	v_pk_fma_f32 v[120:121], v[28:29], v[122:123], v[120:121]
	s_nop 0
	v_pk_fma_f32 v[128:129], v[30:31], v[132:133], v[120:121]
	ds_read_b128 v[120:123], v111 offset:624
	v_pk_fma_f32 v[128:129], v[32:33], v[134:135], v[128:129]
	ds_read_b128 v[132:135], v111 offset:640
	s_waitcnt lgkmcnt(2)
	v_pk_fma_f32 v[128:129], v[34:35], v[142:143], v[128:129]
	s_nop 0
	v_pk_fma_f32 v[128:129], v[36:37], v[144:145], v[128:129]
	ds_read_b128 v[142:145], v111 offset:656
	s_waitcnt lgkmcnt(2)
	v_pk_fma_f32 v[120:121], v[38:39], v[120:121], v[128:129]
	s_nop 0
	v_pk_fma_f32 v[120:121], v[40:41], v[122:123], v[120:121]
	s_waitcnt lgkmcnt(1)
	v_pk_fma_f32 v[128:129], v[42:43], v[132:133], v[120:121]
	ds_read_b128 v[120:123], v111 offset:672
	v_pk_fma_f32 v[128:129], v[44:45], v[134:135], v[128:129]
	ds_read_b128 v[132:135], v111 offset:688
	s_waitcnt lgkmcnt(2)
	v_pk_fma_f32 v[128:129], v[46:47], v[142:143], v[128:129]
	s_nop 0
	v_pk_fma_f32 v[128:129], v[48:49], v[144:145], v[128:129]
	ds_read_b128 v[142:145], v111 offset:704
	s_waitcnt lgkmcnt(2)
	v_pk_fma_f32 v[120:121], v[50:51], v[120:121], v[128:129]
	s_nop 0
	v_pk_fma_f32 v[120:121], v[52:53], v[122:123], v[120:121]
	s_waitcnt lgkmcnt(1)
	v_pk_fma_f32 v[120:121], v[54:55], v[132:133], v[120:121]
	s_nop 0
	v_pk_fma_f32 v[128:129], v[56:57], v[134:135], v[120:121]
	ds_read_b128 v[120:123], v111 offset:720
	ds_read_b128 v[132:135], v111 offset:736
	s_waitcnt lgkmcnt(2)
	v_pk_fma_f32 v[128:129], v[58:59], v[142:143], v[128:129]
	s_nop 0
	v_pk_fma_f32 v[128:129], v[60:61], v[144:145], v[128:129]
	ds_read_b128 v[142:145], v111 offset:752
	s_waitcnt lgkmcnt(2)
	v_pk_fma_f32 v[120:121], v[62:63], v[120:121], v[128:129]
	s_nop 0
	v_pk_fma_f32 v[120:121], v[64:65], v[122:123], v[120:121]

	s_waitcnt lgkmcnt(1)
	v_pk_fma_f32 v[120:121], v[66:67], v[132:133], v[120:121]

	v_pk_fma_f32 v[120:121], v[68:69], v[134:135], v[120:121]
	v_rcp_f32_e32 v122, v109
	s_nop 0
	v_mul_f32_e32 v109, v136, v122
	s_waitcnt lgkmcnt(0)
	v_pk_fma_f32 v[120:121], v[70:71], v[142:143], v[120:121]
	s_nop 0
	v_pk_fma_f32 v[120:121], v[8:9], v[144:145], v[120:121]
	s_nop 0
	v_add_f32_e32 v120, v120, v121
	ds_write_b32 v105, v120 offset:5376
	s_waitcnt lgkmcnt(0)
	s_barrier
	ds_read2st64_b32 v[120:121], v131 offset0:21 offset1:23
	s_waitcnt lgkmcnt(0)
	v_add_f32_e32 v120, v120, v121
	v_fma_f32 v109, -v72, v120, v109
	v_mul_f32_e32 v128, v73, v109
	ds_read_b128 v[120:123], v111 offset:512
	ds_read_b128 v[132:135], v111 offset:528
	ds_read_b128 v[142:145], v111 offset:544
	ds_read_b128 v[146:149], v111 offset:560
	ds_read_b128 v[150:153], v111 offset:2560
	s_waitcnt lgkmcnt(4)
	v_pk_mul_f32 v[120:121], v[120:121], v[128:129] op_sel_hi:[1,0]
	s_waitcnt lgkmcnt(3)
	v_pk_mul_f32 v[132:133], v[132:133], v[128:129] op_sel_hi:[1,0]
	v_pk_fma_f32 v[10:11], v[72:73], v[10:11], v[120:121] op_sel_hi:[0,1,1]
	v_pk_mul_f32 v[120:121], v[122:123], v[128:129] op_sel_hi:[1,0]
	s_waitcnt lgkmcnt(0)
	v_pk_fma_f32 v[136:137], v[150:151], v[10:11], 0 op_sel_hi:[1,1,0]
	v_pk_fma_f32 v[12:13], v[72:73], v[12:13], v[120:121] op_sel_hi:[0,1,1]
	ds_read_b128 v[120:123], v111 offset:2576
	v_pk_fma_f32 v[136:137], v[152:153], v[12:13], v[136:137]
	v_pk_fma_f32 v[14:15], v[72:73], v[14:15], v[132:133] op_sel_hi:[0,1,1]
	v_pk_mul_f32 v[132:133], v[134:135], v[128:129] op_sel_hi:[1,0]
	s_waitcnt lgkmcnt(0)
	v_pk_fma_f32 v[120:121], v[120:121], v[14:15], v[136:137]
	v_pk_fma_f32 v[16:17], v[72:73], v[16:17], v[132:133] op_sel_hi:[0,1,1]
	v_pk_fma_f32 v[136:137], v[122:123], v[16:17], v[120:121]
	ds_read_b128 v[120:123], v111 offset:2592
	v_pk_mul_f32 v[132:133], v[128:129], v[142:143] op_sel_hi:[0,1]
	v_pk_fma_f32 v[18:19], v[72:73], v[18:19], v[132:133] op_sel_hi:[0,1,1]
	v_pk_mul_f32 v[132:133], v[128:129], v[144:145] op_sel_hi:[0,1]
	v_pk_fma_f32 v[20:21], v[72:73], v[20:21], v[132:133] op_sel_hi:[0,1,1]
	ds_read_b128 v[132:135], v111 offset:2608
	s_waitcnt lgkmcnt(1)
	v_pk_fma_f32 v[120:121], v[120:121], v[18:19], v[136:137]
	s_nop 0
	v_pk_fma_f32 v[136:137], v[122:123], v[20:21], v[120:121]
	v_pk_mul_f32 v[120:121], v[128:129], v[146:147] op_sel_hi:[0,1]
	v_pk_fma_f32 v[22:23], v[72:73], v[22:23], v[120:121] op_sel_hi:[0,1,1]
	v_pk_mul_f32 v[120:121], v[128:129], v[148:149] op_sel_hi:[0,1]
	v_pk_fma_f32 v[24:25], v[72:73], v[24:25], v[120:121] op_sel_hi:[0,1,1]
	ds_read_b128 v[120:123], v111 offset:576
	s_waitcnt lgkmcnt(1)
	v_pk_fma_f32 v[132:133], v[132:133], v[22:23], v[136:137]
	s_waitcnt lgkmcnt(0)
	v_pk_mul_f32 v[120:121], v[128:129], v[120:121] op_sel_hi:[0,1]
	v_pk_fma_f32 v[136:137], v[134:135], v[24:25], v[132:133]
	ds_read_b128 v[132:135], v111 offset:2624
	ds_read_b128 v[142:145], v111 offset:592
	v_pk_fma_f32 v[26:27], v[72:73], v[26:27], v[120:121] op_sel_hi:[0,1,1]
	v_pk_mul_f32 v[120:121], v[128:129], v[122:123] op_sel_hi:[0,1]
	v_pk_fma_f32 v[28:29], v[72:73], v[28:29], v[120:121] op_sel_hi:[0,1,1]
	ds_read_b128 v[120:123], v111 offset:2640
	s_waitcnt lgkmcnt(2)
	v_pk_fma_f32 v[132:133], v[132:133], v[26:27], v[136:137]
	s_nop 0
	v_pk_fma_f32 v[136:137], v[134:135], v[28:29], v[132:133]
	s_waitcnt lgkmcnt(1)
	v_pk_mul_f32 v[132:133], v[128:129], v[142:143] op_sel_hi:[0,1]
	v_pk_fma_f32 v[30:31], v[72:73], v[30:31], v[132:133] op_sel_hi:[0,1,1]
	v_pk_mul_f32 v[132:133], v[128:129], v[144:145] op_sel_hi:[0,1]
	v_pk_fma_f32 v[32:33], v[72:73], v[32:33], v[132:133] op_sel_hi:[0,1,1]
	ds_read_b128 v[132:135], v111 offset:608
	s_waitcnt lgkmcnt(1)
	v_pk_fma_f32 v[120:121], v[120:121], v[30:31], v[136:137]
	s_waitcnt lgkmcnt(0)
	v_pk_mul_f32 v[132:133], v[128:129], v[132:133] op_sel_hi:[0,1]
	v_pk_fma_f32 v[136:137], v[122:123], v[32:33], v[120:121]
	ds_read_b128 v[120:123], v111 offset:2656
	ds_read_b128 v[142:145], v111 offset:624
	v_pk_fma_f32 v[34:35], v[72:73], v[34:35], v[132:133] op_sel_hi:[0,1,1]
	v_pk_mul_f32 v[132:133], v[128:129], v[134:135] op_sel_hi:[0,1]
	v_pk_fma_f32 v[36:37], v[72:73], v[36:37], v[132:133] op_sel_hi:[0,1,1]
	ds_read_b128 v[132:135], v111 offset:2672
	s_waitcnt lgkmcnt(2)
	v_pk_fma_f32 v[120:121], v[120:121], v[34:35], v[136:137]
	s_nop 0
	v_pk_fma_f32 v[136:137], v[122:123], v[36:37], v[120:121]
	s_waitcnt lgkmcnt(1)
	v_pk_mul_f32 v[120:121], v[128:129], v[142:143] op_sel_hi:[0,1]
	v_pk_fma_f32 v[38:39], v[72:73], v[38:39], v[120:121] op_sel_hi:[0,1,1]
	v_pk_mul_f32 v[120:121], v[128:129], v[144:145] op_sel_hi:[0,1]
	v_pk_fma_f32 v[40:41], v[72:73], v[40:41], v[120:121] op_sel_hi:[0,1,1]
	ds_read_b128 v[120:123], v111 offset:640
	s_waitcnt lgkmcnt(1)
	v_pk_fma_f32 v[132:133], v[132:133], v[38:39], v[136:137]
	s_waitcnt lgkmcnt(0)
	v_pk_mul_f32 v[120:121], v[128:129], v[120:121] op_sel_hi:[0,1]
	v_pk_fma_f32 v[136:137], v[134:135], v[40:41], v[132:133]
	ds_read_b128 v[132:135], v111 offset:2688
	ds_read_b128 v[142:145], v111 offset:656
	v_pk_fma_f32 v[42:43], v[72:73], v[42:43], v[120:121] op_sel_hi:[0,1,1]
	v_pk_mul_f32 v[120:121], v[128:129], v[122:123] op_sel_hi:[0,1]
	v_pk_fma_f32 v[44:45], v[72:73], v[44:45], v[120:121] op_sel_hi:[0,1,1]
	ds_read_b128 v[120:123], v111 offset:2704
	s_waitcnt lgkmcnt(2)
	v_pk_fma_f32 v[132:133], v[132:133], v[42:43], v[136:137]
	s_nop 0
	v_pk_fma_f32 v[136:137], v[134:135], v[44:45], v[132:133]
	s_waitcnt lgkmcnt(1)
	v_pk_mul_f32 v[132:133], v[128:129], v[142:143] op_sel_hi:[0,1]
	v_pk_fma_f32 v[46:47], v[72:73], v[46:47], v[132:133] op_sel_hi:[0,1,1]
	v_pk_mul_f32 v[132:133], v[128:129], v[144:145] op_sel_hi:[0,1]
	v_pk_fma_f32 v[48:49], v[72:73], v[48:49], v[132:133] op_sel_hi:[0,1,1]
	ds_read_b128 v[132:135], v111 offset:672
	s_waitcnt lgkmcnt(1)
	v_pk_fma_f32 v[120:121], v[120:121], v[46:47], v[136:137]
	s_waitcnt lgkmcnt(0)
	v_pk_mul_f32 v[132:133], v[128:129], v[132:133] op_sel_hi:[0,1]
	v_pk_fma_f32 v[136:137], v[122:123], v[48:49], v[120:121]
	ds_read_b128 v[120:123], v111 offset:2720
	ds_read_b128 v[142:145], v111 offset:688
	v_pk_fma_f32 v[50:51], v[72:73], v[50:51], v[132:133] op_sel_hi:[0,1,1]
	v_pk_mul_f32 v[132:133], v[128:129], v[134:135] op_sel_hi:[0,1]
	v_pk_fma_f32 v[52:53], v[72:73], v[52:53], v[132:133] op_sel_hi:[0,1,1]
	ds_read_b128 v[132:135], v111 offset:2736
	s_waitcnt lgkmcnt(2)
	v_pk_fma_f32 v[120:121], v[120:121], v[50:51], v[136:137]
	s_nop 0
	v_pk_fma_f32 v[136:137], v[122:123], v[52:53], v[120:121]
	s_waitcnt lgkmcnt(1)
	v_pk_mul_f32 v[120:121], v[128:129], v[142:143] op_sel_hi:[0,1]
	v_pk_fma_f32 v[54:55], v[72:73], v[54:55], v[120:121] op_sel_hi:[0,1,1]
	v_pk_mul_f32 v[120:121], v[128:129], v[144:145] op_sel_hi:[0,1]
	v_pk_fma_f32 v[56:57], v[72:73], v[56:57], v[120:121] op_sel_hi:[0,1,1]
	ds_read_b128 v[120:123], v111 offset:704
	s_waitcnt lgkmcnt(1)
	v_pk_fma_f32 v[132:133], v[132:133], v[54:55], v[136:137]
	s_waitcnt lgkmcnt(0)
	v_pk_mul_f32 v[120:121], v[128:129], v[120:121] op_sel_hi:[0,1]
	v_pk_fma_f32 v[136:137], v[134:135], v[56:57], v[132:133]
	ds_read_b128 v[132:135], v111 offset:2752
	ds_read_b128 v[142:145], v111 offset:720
	v_pk_fma_f32 v[58:59], v[72:73], v[58:59], v[120:121] op_sel_hi:[0,1,1]
	v_pk_mul_f32 v[120:121], v[128:129], v[122:123] op_sel_hi:[0,1]
	v_pk_fma_f32 v[60:61], v[72:73], v[60:61], v[120:121] op_sel_hi:[0,1,1]
	s_waitcnt lgkmcnt(1)
	v_pk_fma_f32 v[132:133], v[132:133], v[58:59], v[136:137]
	ds_read_b128 v[120:123], v111 offset:2768
	v_pk_fma_f32 v[136:137], v[134:135], v[60:61], v[132:133]
	s_waitcnt lgkmcnt(1)
	v_pk_mul_f32 v[132:133], v[128:129], v[142:143] op_sel_hi:[0,1]
	v_pk_fma_f32 v[62:63], v[72:73], v[62:63], v[132:133] op_sel_hi:[0,1,1]
	v_pk_mul_f32 v[132:133], v[128:129], v[144:145] op_sel_hi:[0,1]
	v_pk_fma_f32 v[64:65], v[72:73], v[64:65], v[132:133] op_sel_hi:[0,1,1]
	ds_read_b128 v[132:135], v111 offset:736
	s_waitcnt lgkmcnt(1)
	v_pk_fma_f32 v[120:121], v[120:121], v[62:63], v[136:137]
	s_waitcnt lgkmcnt(0)
	v_pk_mul_f32 v[132:133], v[128:129], v[132:133] op_sel_hi:[0,1]
	v_pk_fma_f32 v[136:137], v[122:123], v[64:65], v[120:121]
	ds_read_b128 v[120:123], v111 offset:2784
	ds_read_b128 v[142:145], v111 offset:752
	v_pk_fma_f32 v[66:67], v[72:73], v[66:67], v[132:133] op_sel_hi:[0,1,1]
	v_pk_mul_f32 v[132:133], v[128:129], v[134:135] op_sel_hi:[0,1]
	v_pk_fma_f32 v[68:69], v[72:73], v[68:69], v[132:133] op_sel_hi:[0,1,1]
	ds_read_b128 v[132:135], v111 offset:2800
	s_waitcnt lgkmcnt(2)
	v_pk_fma_f32 v[120:121], v[120:121], v[66:67], v[136:137]
	s_nop 0
	v_pk_fma_f32 v[120:121], v[122:123], v[68:69], v[120:121]
	s_waitcnt lgkmcnt(1)
	v_pk_mul_f32 v[122:123], v[128:129], v[142:143] op_sel_hi:[0,1]
	v_pk_fma_f32 v[70:71], v[72:73], v[70:71], v[122:123] op_sel_hi:[0,1,1]
	v_pk_mul_f32 v[122:123], v[128:129], v[144:145] op_sel_hi:[0,1]
	v_pk_fma_f32 v[8:9], v[72:73], v[8:9], v[122:123] op_sel_hi:[0,1,1]
	s_waitcnt lgkmcnt(0)
	v_pk_fma_f32 v[72:73], v[132:133], v[70:71], v[120:121]
	s_nop 0
	v_pk_fma_f32 v[72:73], v[134:135], v[8:9], v[72:73]
	s_nop 0
	v_add_f32_e32 v73, v72, v73
	s_and_saveexec_b64 s[52:53], s[8:9]
	ds_write_b32 v105, v73 offset:8448
	s_or_b64 exec, exec, s[52:53]
	v_add_f32_e32 v72, 0, v116
	v_add_f32_e32 v72, v72, v117
	v_add_f32_e32 v72, v72, v118
	v_add_f32_e32 v72, v72, v119
	v_mul_f32_e32 v72, 0xbfb8aa3b, v72
	v_exp_f32_e32 v72, v72
	v_mul_f32_e32 v136, v76, v130
	v_fmac_f32_e32 v136, v107, v77
	v_lshlrev_b32_e32 v108, 16, v108
	v_add_f32_e32 v116, 1.0, v72
	v_fmac_f32_e32 v136, v75, v110

	v_fmac_f32_e32 v136, v74, v108

	v_mul_f32_e32 v107, 0xbfb8aa3b, v136
	v_exp_f32_e32 v107, v107
	v_mul_f32_e32 v109, v126, v127
	v_mul_f32_e32 v109, 0x3fb8aa3b, v109

	v_exp_f32_e32 v72, v109


	v_add_f32_e32 v107, 1.0, v107


	v_rcp_f32_e32 v109, v116
	s_nop 0
	v_mul_f32_e32 v109, 1.0, v109


	ds_read_b128 v[116:119], v111 offset:1024


	ds_read_b128 v[120:123], v111 offset:1040
	ds_read_b128 v[126:129], v111 offset:1056
	ds_read_b128 v[132:135], v111 offset:1072
	s_waitcnt lgkmcnt(3)
	v_pk_fma_f32 v[116:117], v[10:11], v[116:117], 0 op_sel_hi:[1,1,0]
	s_nop 0
	v_pk_fma_f32 v[116:117], v[12:13], v[118:119], v[116:117]
	s_waitcnt lgkmcnt(2)
	v_pk_fma_f32 v[116:117], v[14:15], v[120:121], v[116:117]
	s_nop 0
	v_pk_fma_f32 v[116:117], v[16:17], v[122:123], v[116:117]
	s_waitcnt lgkmcnt(1)
	v_pk_fma_f32 v[120:121], v[18:19], v[126:127], v[116:117]
	ds_read_b128 v[116:119], v111 offset:1088
	v_pk_fma_f32 v[120:121], v[20:21], v[128:129], v[120:121]
	s_waitcnt lgkmcnt(1)
	v_pk_fma_f32 v[126:127], v[22:23], v[132:133], v[120:121]
	ds_read_b128 v[120:123], v111 offset:1104
	v_pk_fma_f32 v[126:127], v[24:25], v[134:135], v[126:127]
	s_waitcnt lgkmcnt(1)
	v_pk_fma_f32 v[116:117], v[26:27], v[116:117], v[126:127]
	ds_read_b128 v[126:129], v111 offset:1120
	v_pk_fma_f32 v[116:117], v[28:29], v[118:119], v[116:117]
	s_waitcnt lgkmcnt(1)
	v_pk_fma_f32 v[120:121], v[30:31], v[120:121], v[116:117]
	ds_read_b128 v[116:119], v111 offset:1136
	v_pk_fma_f32 v[120:121], v[32:33], v[122:123], v[120:121]
	s_waitcnt lgkmcnt(1)
	v_pk_fma_f32 v[126:127], v[34:35], v[126:127], v[120:121]
	ds_read_b128 v[120:123], v111 offset:1152
	v_pk_fma_f32 v[126:127], v[36:37], v[128:129], v[126:127]
	s_waitcnt lgkmcnt(1)
	v_pk_fma_f32 v[116:117], v[38:39], v[116:117], v[126:127]
	ds_read_b128 v[126:129], v111 offset:1168
	v_pk_fma_f32 v[116:117], v[40:41], v[118:119], v[116:117]
	s_waitcnt lgkmcnt(1)
	v_pk_fma_f32 v[120:121], v[42:43], v[120:121], v[116:117]
	ds_read_b128 v[116:119], v111 offset:1184
	v_pk_fma_f32 v[120:121], v[44:45], v[122:123], v[120:121]
	s_waitcnt lgkmcnt(1)
	v_pk_fma_f32 v[126:127], v[46:47], v[126:127], v[120:121]
	ds_read_b128 v[120:123], v111 offset:1200
	v_pk_fma_f32 v[126:127], v[48:49], v[128:129], v[126:127]
	s_waitcnt lgkmcnt(1)
	v_pk_fma_f32 v[116:117], v[50:51], v[116:117], v[126:127]
	ds_read_b128 v[126:129], v111 offset:1216
	v_pk_fma_f32 v[116:117], v[52:53], v[118:119], v[116:117]
	s_waitcnt lgkmcnt(1)
	v_pk_fma_f32 v[116:117], v[54:55], v[120:121], v[116:117]
	s_nop 0
	v_pk_fma_f32 v[120:121], v[56:57], v[122:123], v[116:117]
	ds_read_b128 v[116:119], v111 offset:1232
	s_waitcnt lgkmcnt(1)
	v_pk_fma_f32 v[126:127], v[58:59], v[126:127], v[120:121]
	ds_read_b128 v[120:123], v111 offset:1248
	v_pk_fma_f32 v[132:133], v[60:61], v[128:129], v[126:127]
	ds_read_b128 v[126:129], v111 offset:1264
	s_waitcnt lgkmcnt(2)
	v_pk_fma_f32 v[116:117], v[62:63], v[116:117], v[132:133]
	s_nop 0
	v_pk_fma_f32 v[116:117], v[64:65], v[118:119], v[116:117]

; DEV void gdn_sample_item(const Params& p, int item, unsigned char* lds) {
;     ...
; #pragma unroll
;         for (int d4 = 0; d4 < 16; ++d4) { const f32x4 k4 = *(const f32x4*)(kk + d4 * 4); ks2 += (f32x2_t){k4[0], k4[1]} * S[d4 * 2]; ks2 += (f32x2_t){k4[2], k4[3]} * S[d4 * 2 + 1]; }
	s_waitcnt lgkmcnt(1)
	v_pk_fma_f32 v[116:117], v[66:67], v[120:121], v[116:117]

; DEV void gdn_sample_item(const Params& p, int item, unsigned char* lds) {
;     ...
;         for (int d4 = 0; d4 < 16; ++d4) { const f32x4 k4 = *(const f32x4*)(kk + d4 * 4); ks2 += (f32x2_t){k4[0], k4[1]} * S[d4 * 2]; ks2 += (f32x2_t){k4[2], k4[3]} * S[d4 * 2 + 1]; }
;         part[(t * 2 + half) * 128 + c] = ks2[0] + ks2[1];
;         __syncthreads();
;         const float kS = part[(t * 2) * 128 + c] + part[(t * 2 + 1) * 128 + c];
;         const float eg = gt[t], dl = bt[t] * (vv[t] - eg * kS);
;         const f32x2_t eg2 = {eg, eg}, dl2 = {dl, dl};
;         f32x2_t o2 = {0.f, 0.f};
; #pragma unroll
;         for (int d4 = 0; d4 < 16; ++d4) {
;             const f32x4 k4 = *(const f32x4*)(kk + d4 * 4), q4 = *(const f32x4*)(qq + d4 * 4);
;             const f32x2_t s0 = S[d4 * 2] * eg2 + (f32x2_t){k4[0], k4[1]} * dl2, s1 = S[d4 * 2 + 1] * eg2 + (f32x2_t){k4[2], k4[3]} * dl2;
;             S[d4 * 2] = s0; S[d4 * 2 + 1] = s1;
;             o2 += (f32x2_t){q4[0], q4[1]} * s0; o2 += (f32x2_t){q4[2], q4[3]} * s1;
;         }
	v_pk_fma_f32 v[116:117], v[68:69], v[122:123], v[116:117]
	v_rcp_f32_e32 v118, v107
	s_nop 0
	v_mul_f32_e32 v107, v136, v118
	s_waitcnt lgkmcnt(0)
	v_pk_fma_f32 v[116:117], v[70:71], v[126:127], v[116:117]
	s_nop 0
	v_pk_fma_f32 v[116:117], v[8:9], v[128:129], v[116:117]
	s_nop 0
	v_add_f32_e32 v116, v116, v117
	ds_write_b32 v105, v116 offset:6400
	s_waitcnt lgkmcnt(0)
	s_barrier
	ds_read2st64_b32 v[116:117], v131 offset0:25 offset1:27
	s_waitcnt lgkmcnt(0)
	v_add_f32_e32 v116, v116, v117
	v_fma_f32 v107, -v72, v116, v107
	v_mul_f32_e32 v136, v109, v107
	ds_read_b128 v[116:119], v111 offset:1024
	ds_read_b128 v[120:123], v111 offset:1040
	ds_read_b128 v[126:129], v111 offset:1056
	ds_read_b128 v[132:135], v111 offset:1072
	ds_read_b128 v[142:145], v111 offset:3072
	s_waitcnt lgkmcnt(4)
	v_pk_mul_f32 v[116:117], v[116:117], v[136:137] op_sel_hi:[1,0]
	s_waitcnt lgkmcnt(3)
	v_pk_mul_f32 v[120:121], v[120:121], v[136:137] op_sel_hi:[1,0]
	v_pk_fma_f32 v[10:11], v[72:73], v[10:11], v[116:117] op_sel_hi:[0,1,1]
	v_pk_mul_f32 v[116:117], v[118:119], v[136:137] op_sel_hi:[1,0]
	s_waitcnt lgkmcnt(0)
	v_pk_fma_f32 v[142:143], v[142:143], v[10:11], 0 op_sel_hi:[1,1,0]
	v_pk_fma_f32 v[12:13], v[72:73], v[12:13], v[116:117] op_sel_hi:[0,1,1]
	ds_read_b128 v[116:119], v111 offset:3088
	v_pk_fma_f32 v[142:143], v[144:145], v[12:13], v[142:143]
	v_pk_fma_f32 v[14:15], v[72:73], v[14:15], v[120:121] op_sel_hi:[0,1,1]
	v_pk_mul_f32 v[120:121], v[122:123], v[136:137] op_sel_hi:[1,0]
	s_waitcnt lgkmcnt(0)
	v_pk_fma_f32 v[116:117], v[116:117], v[14:15], v[142:143]
	v_pk_fma_f32 v[16:17], v[72:73], v[16:17], v[120:121] op_sel_hi:[0,1,1]
	v_pk_fma_f32 v[142:143], v[118:119], v[16:17], v[116:117]
	ds_read_b128 v[116:119], v111 offset:3104
	v_pk_mul_f32 v[120:121], v[136:137], v[126:127] op_sel_hi:[0,1]
	v_pk_fma_f32 v[18:19], v[72:73], v[18:19], v[120:121] op_sel_hi:[0,1,1]
	v_pk_mul_f32 v[120:121], v[136:137], v[128:129] op_sel_hi:[0,1]
	v_pk_fma_f32 v[20:21], v[72:73], v[20:21], v[120:121] op_sel_hi:[0,1,1]
	ds_read_b128 v[120:123], v111 offset:3120
	s_waitcnt lgkmcnt(1)
	v_pk_fma_f32 v[116:117], v[116:117], v[18:19], v[142:143]
	s_nop 0
	v_pk_fma_f32 v[126:127], v[118:119], v[20:21], v[116:117]
	v_pk_mul_f32 v[116:117], v[136:137], v[132:133] op_sel_hi:[0,1]
	v_pk_fma_f32 v[22:23], v[72:73], v[22:23], v[116:117] op_sel_hi:[0,1,1]
	v_pk_mul_f32 v[116:117], v[136:137], v[134:135] op_sel_hi:[0,1]
	v_pk_fma_f32 v[24:25], v[72:73], v[24:25], v[116:117] op_sel_hi:[0,1,1]
	ds_read_b128 v[116:119], v111 offset:1088
	s_waitcnt lgkmcnt(1)
	v_pk_fma_f32 v[120:121], v[120:121], v[22:23], v[126:127]
	s_waitcnt lgkmcnt(0)
	v_pk_mul_f32 v[116:117], v[136:137], v[116:117] op_sel_hi:[0,1]
	v_pk_fma_f32 v[132:133], v[122:123], v[24:25], v[120:121]
	ds_read_b128 v[120:123], v111 offset:3136
	ds_read_b128 v[126:129], v111 offset:1104
	v_pk_fma_f32 v[26:27], v[72:73], v[26:27], v[116:117] op_sel_hi:[0,1,1]
	v_pk_mul_f32 v[116:117], v[136:137], v[118:119] op_sel_hi:[0,1]
	v_pk_fma_f32 v[28:29], v[72:73], v[28:29], v[116:117] op_sel_hi:[0,1,1]
	ds_read_b128 v[116:119], v111 offset:3152
	s_waitcnt lgkmcnt(2)
	v_pk_fma_f32 v[120:121], v[120:121], v[26:27], v[132:133]
	s_nop 0
	v_pk_fma_f32 v[132:133], v[122:123], v[28:29], v[120:121]
	s_waitcnt lgkmcnt(1)
	v_pk_mul_f32 v[120:121], v[136:137], v[126:127] op_sel_hi:[0,1]
	v_pk_fma_f32 v[30:31], v[72:73], v[30:31], v[120:121] op_sel_hi:[0,1,1]
	v_pk_mul_f32 v[120:121], v[136:137], v[128:129] op_sel_hi:[0,1]
	v_pk_fma_f32 v[32:33], v[72:73], v[32:33], v[120:121] op_sel_hi:[0,1,1]
	ds_read_b128 v[120:123], v111 offset:1120
	s_waitcnt lgkmcnt(1)
	v_pk_fma_f32 v[116:117], v[116:117], v[30:31], v[132:133]
	s_waitcnt lgkmcnt(0)
	v_pk_mul_f32 v[120:121], v[136:137], v[120:121] op_sel_hi:[0,1]
	v_pk_fma_f32 v[132:133], v[118:119], v[32:33], v[116:117]
	ds_read_b128 v[116:119], v111 offset:3168
	ds_read_b128 v[126:129], v111 offset:1136
	v_pk_fma_f32 v[34:35], v[72:73], v[34:35], v[120:121] op_sel_hi:[0,1,1]
	v_pk_mul_f32 v[120:121], v[136:137], v[122:123] op_sel_hi:[0,1]
	v_pk_fma_f32 v[36:37], v[72:73], v[36:37], v[120:121] op_sel_hi:[0,1,1]
	ds_read_b128 v[120:123], v111 offset:3184
	s_waitcnt lgkmcnt(2)
	v_pk_fma_f32 v[116:117], v[116:117], v[34:35], v[132:133]
	s_nop 0
	v_pk_fma_f32 v[132:133], v[118:119], v[36:37], v[116:117]
	s_waitcnt lgkmcnt(1)
	v_pk_mul_f32 v[116:117], v[136:137], v[126:127] op_sel_hi:[0,1]
	v_pk_fma_f32 v[38:39], v[72:73], v[38:39], v[116:117] op_sel_hi:[0,1,1]
	v_pk_mul_f32 v[116:117], v[136:137], v[128:129] op_sel_hi:[0,1]
	v_pk_fma_f32 v[40:41], v[72:73], v[40:41], v[116:117] op_sel_hi:[0,1,1]
	ds_read_b128 v[116:119], v111 offset:1152
	s_waitcnt lgkmcnt(1)
	v_pk_fma_f32 v[120:121], v[120:121], v[38:39], v[132:133]
	s_waitcnt lgkmcnt(0)
; DEV float silu_f(float x) { return x / (1.f + __expf(-x)); }
; DEV void gdn_sample_item(const Params& p, int item, unsigned char* lds) {
;     ...
;             const float y = silu_f(wj[0] * x[t] + wj[1] * x[t + 1] + wj[2] * x[t + 2] + wj[3] * x[t + 3]);
;             if (m == 0) qv[t] = y; else if (m == 1) kv[t] = y; else vv[t] = y;
;         }
;     }
; #pragma unroll
;     for (int t = 0; t < 4; ++t) {
;         const float a = wave_sum(qv[t] * qv[t]), bq = wave_sum(kv[t] * kv[t]);
;         if (lane == 0) { red[wid * 8 + t] = a; red[wid * 8 + 4 + t] = bq; }
;     }
;     __syncthreads();
;     float gt[4], bt[4];
; #pragma unroll
;     for (int t = 0; t < 4; ++t) {
;         const float sq = red[(2 * half) * 8 + t] + red[(2 * half + 1) * 8 + t], sk = red[(2 * half) * 8 + 4 + t] + red[(2 * half + 1) * 8 + 4 + t];
;         if (half == 0) {
;             qsh[t * 128 + c] = qv[t] * rsqrtf(sq + EPS) * 0.08838834764831845f;
;             ksh[t * 128 + c] = kv[t] * rsqrtf(sk + EPS);
;         }
;         float a = 0.f, bb = 0.f;
; #pragma unroll
;         for (int kq = 0; kq < 4; ++kq) { a += ab[(size_t)kq * TT * 16 + (size_t)(r0 + t) * 16 + h]; bb += ab[(size_t)kq * TT * 16 + (size_t)(r0 + t) * 16 + 8 + h]; }
;         const float xx = a + p.in[12][h];
;         const float sp = xx > 20.f ? xx : log1pf(__expf(xx));
;         gt[t] = __expf(-__expf(p.in[11][h]) * sp);
;         bt[t] = 1.f / (1.f + __expf(-bb));
;     ...
;         for (int d4 = 0; d4 < 16; ++d4) {
;             const f32x4 k4 = *(const f32x4*)(kk + d4 * 4), q4 = *(const f32x4*)(qq + d4 * 4);
;             const f32x2_t s0 = S[d4 * 2] * eg2 + (f32x2_t){k4[0], k4[1]} * dl2, s1 = S[d4 * 2 + 1] * eg2 + (f32x2_t){k4[2], k4[3]} * dl2;
;             S[d4 * 2] = s0; S[d4 * 2 + 1] = s1;
;             o2 += (f32x2_t){q4[0], q4[1]} * s0; o2 += (f32x2_t){q4[2], q4[3]} * s1;
;         }
;         const float o = o2[0] + o2[1];
;         ot[t] = o;
;         if (half == 1) opart[t * 128 + c] = o;
	v_pk_mul_f32 v[116:117], v[136:137], v[116:117] op_sel_hi:[0,1]
	v_pk_fma_f32 v[132:133], v[122:123], v[40:41], v[120:121]
	ds_read_b128 v[120:123], v111 offset:3200
	ds_read_b128 v[126:129], v111 offset:1168
	v_pk_fma_f32 v[42:43], v[72:73], v[42:43], v[116:117] op_sel_hi:[0,1,1]
	v_pk_mul_f32 v[116:117], v[136:137], v[118:119] op_sel_hi:[0,1]
	v_pk_fma_f32 v[44:45], v[72:73], v[44:45], v[116:117] op_sel_hi:[0,1,1]
	ds_read_b128 v[116:119], v111 offset:3216
	s_waitcnt lgkmcnt(2)
	v_pk_fma_f32 v[120:121], v[120:121], v[42:43], v[132:133]
	s_nop 0
	v_pk_fma_f32 v[132:133], v[122:123], v[44:45], v[120:121]
	s_waitcnt lgkmcnt(1)
	v_pk_mul_f32 v[120:121], v[136:137], v[126:127] op_sel_hi:[0,1]
	v_pk_fma_f32 v[46:47], v[72:73], v[46:47], v[120:121] op_sel_hi:[0,1,1]
	v_pk_mul_f32 v[120:121], v[136:137], v[128:129] op_sel_hi:[0,1]
	v_pk_fma_f32 v[48:49], v[72:73], v[48:49], v[120:121] op_sel_hi:[0,1,1]
	ds_read_b128 v[120:123], v111 offset:1184
	s_waitcnt lgkmcnt(1)
	v_pk_fma_f32 v[116:117], v[116:117], v[46:47], v[132:133]
	s_waitcnt lgkmcnt(0)
	v_pk_mul_f32 v[120:121], v[136:137], v[120:121] op_sel_hi:[0,1]
	v_pk_fma_f32 v[132:133], v[118:119], v[48:49], v[116:117]
	ds_read_b128 v[116:119], v111 offset:3232
	ds_read_b128 v[126:129], v111 offset:1200
	v_pk_fma_f32 v[50:51], v[72:73], v[50:51], v[120:121] op_sel_hi:[0,1,1]
	v_pk_mul_f32 v[120:121], v[136:137], v[122:123] op_sel_hi:[0,1]
	v_pk_fma_f32 v[52:53], v[72:73], v[52:53], v[120:121] op_sel_hi:[0,1,1]
	ds_read_b128 v[120:123], v111 offset:3248
	s_waitcnt lgkmcnt(2)
	v_pk_fma_f32 v[116:117], v[116:117], v[50:51], v[132:133]
	s_nop 0
	v_pk_fma_f32 v[132:133], v[118:119], v[52:53], v[116:117]
	s_waitcnt lgkmcnt(1)
	v_pk_mul_f32 v[116:117], v[136:137], v[126:127] op_sel_hi:[0,1]
	v_pk_fma_f32 v[54:55], v[72:73], v[54:55], v[116:117] op_sel_hi:[0,1,1]
	v_pk_mul_f32 v[116:117], v[136:137], v[128:129] op_sel_hi:[0,1]
	v_pk_fma_f32 v[56:57], v[72:73], v[56:57], v[116:117] op_sel_hi:[0,1,1]
	ds_read_b128 v[116:119], v111 offset:1216
	s_waitcnt lgkmcnt(1)
	v_pk_fma_f32 v[120:121], v[120:121], v[54:55], v[132:133]
	s_waitcnt lgkmcnt(0)
	v_pk_mul_f32 v[116:117], v[136:137], v[116:117] op_sel_hi:[0,1]
	v_pk_fma_f32 v[132:133], v[122:123], v[56:57], v[120:121]
	ds_read_b128 v[120:123], v111 offset:3264
	ds_read_b128 v[126:129], v111 offset:1232
	v_pk_fma_f32 v[58:59], v[72:73], v[58:59], v[116:117] op_sel_hi:[0,1,1]
	v_pk_mul_f32 v[116:117], v[136:137], v[118:119] op_sel_hi:[0,1]
	v_pk_fma_f32 v[60:61], v[72:73], v[60:61], v[116:117] op_sel_hi:[0,1,1]
	s_waitcnt lgkmcnt(1)
	v_pk_fma_f32 v[120:121], v[120:121], v[58:59], v[132:133]
	ds_read_b128 v[116:119], v111 offset:3280
	v_pk_fma_f32 v[132:133], v[122:123], v[60:61], v[120:121]
	s_waitcnt lgkmcnt(1)
	v_pk_mul_f32 v[120:121], v[136:137], v[126:127] op_sel_hi:[0,1]
	v_pk_fma_f32 v[62:63], v[72:73], v[62:63], v[120:121] op_sel_hi:[0,1,1]
	v_pk_mul_f32 v[120:121], v[136:137], v[128:129] op_sel_hi:[0,1]
	v_pk_fma_f32 v[64:65], v[72:73], v[64:65], v[120:121] op_sel_hi:[0,1,1]
	ds_read_b128 v[120:123], v111 offset:1248
	s_waitcnt lgkmcnt(1)
	v_pk_fma_f32 v[116:117], v[116:117], v[62:63], v[132:133]
	s_waitcnt lgkmcnt(0)
	v_pk_mul_f32 v[120:121], v[136:137], v[120:121] op_sel_hi:[0,1]
	v_pk_fma_f32 v[132:133], v[118:119], v[64:65], v[116:117]
	ds_read_b128 v[116:119], v111 offset:3296
	ds_read_b128 v[126:129], v111 offset:1264
	v_pk_fma_f32 v[66:67], v[72:73], v[66:67], v[120:121] op_sel_hi:[0,1,1]
	v_pk_mul_f32 v[120:121], v[136:137], v[122:123] op_sel_hi:[0,1]
	v_pk_fma_f32 v[68:69], v[72:73], v[68:69], v[120:121] op_sel_hi:[0,1,1]
	ds_read_b128 v[120:123], v111 offset:3312
	s_waitcnt lgkmcnt(2)
	v_pk_fma_f32 v[116:117], v[116:117], v[66:67], v[132:133]
	s_nop 0
	v_pk_fma_f32 v[116:117], v[118:119], v[68:69], v[116:117]
	s_waitcnt lgkmcnt(1)
	v_pk_mul_f32 v[118:119], v[136:137], v[126:127] op_sel_hi:[0,1]
	v_pk_fma_f32 v[70:71], v[72:73], v[70:71], v[118:119] op_sel_hi:[0,1,1]
	v_pk_mul_f32 v[118:119], v[136:137], v[128:129] op_sel_hi:[0,1]
	v_pk_fma_f32 v[8:9], v[72:73], v[8:9], v[118:119] op_sel_hi:[0,1,1]
	s_waitcnt lgkmcnt(0)
	v_pk_fma_f32 v[116:117], v[120:121], v[70:71], v[116:117]
	s_nop 0
	v_pk_fma_f32 v[116:117], v[122:123], v[8:9], v[116:117]
	s_nop 0
	v_add_f32_e32 v107, v116, v117
	s_and_saveexec_b64 s[52:53], s[8:9]
	ds_write_b32 v131, v107 offset:9472
	s_or_b64 exec, exec, s[52:53]
	v_add_f32_e32 v72, 0, v112
	v_add_f32_e32 v72, v72, v113
	v_add_f32_e32 v72, v72, v114
	v_add_f32_e32 v72, v72, v115
	v_mul_f32_e32 v72, 0xbfb8aa3b, v72
	v_exp_f32_e32 v72, v72
	v_mul_f32_e32 v110, v76, v110
	v_fmac_f32_e32 v110, v77, v130
	v_lshlrev_b32_e32 v106, 16, v106
	v_add_f32_e32 v112, 1.0, v72
	v_fmac_f32_e32 v110, v75, v108

; DEV float silu_f(float x) { return x / (1.f + __expf(-x)); }
; DEV void gdn_sample_item(const Params& p, int item, unsigned char* lds) {
;     ...
;             const float y = silu_f(wj[0] * x[t] + wj[1] * x[t + 1] + wj[2] * x[t + 2] + wj[3] * x[t + 3]);
	v_fmac_f32_e32 v110, v74, v106

; DEV float silu_f(float x) { return x / (1.f + __expf(-x)); }
; DEV void gdn_sample_item(const Params& p, int item, unsigned char* lds) {
;     ...
;             const float y = silu_f(wj[0] * x[t] + wj[1] * x[t + 1] + wj[2] * x[t + 2] + wj[3] * x[t + 3]);
;             if (m == 0) qv[t] = y; else if (m == 1) kv[t] = y; else vv[t] = y;
;         }
;     }
; #pragma unroll
;     for (int t = 0; t < 4; ++t) {
;         const float a = wave_sum(qv[t] * qv[t]), bq = wave_sum(kv[t] * kv[t]);
;         if (lane == 0) { red[wid * 8 + t] = a; red[wid * 8 + 4 + t] = bq; }
;     }
;     __syncthreads();
;     float gt[4], bt[4];
; #pragma unroll
;     for (int t = 0; t < 4; ++t) {
;         const float sq = red[(2 * half) * 8 + t] + red[(2 * half + 1) * 8 + t], sk = red[(2 * half) * 8 + 4 + t] + red[(2 * half + 1) * 8 + 4 + t];
;         if (half == 0) {
;             qsh[t * 128 + c] = qv[t] * rsqrtf(sq + EPS) * 0.08838834764831845f;
;             ksh[t * 128 + c] = kv[t] * rsqrtf(sk + EPS);
;         }
;         float a = 0.f, bb = 0.f;
; #pragma unroll
;         for (int kq = 0; kq < 4; ++kq) { a += ab[(size_t)kq * TT * 16 + (size_t)(r0 + t) * 16 + h]; bb += ab[(size_t)kq * TT * 16 + (size_t)(r0 + t) * 16 + 8 + h]; }
;         const float xx = a + p.in[12][h];
;         const float sp = xx > 20.f ? xx : log1pf(__expf(xx));
;         gt[t] = __expf(-__expf(p.in[11][h]) * sp);
;         bt[t] = 1.f / (1.f + __expf(-bb));
	v_mul_f32_e32 v74, 0xbfb8aa3b, v110
	v_exp_f32_e32 v74, v74
	v_mul_f32_e32 v109, v124, v125
	v_mul_f32_e32 v109, 0x3fb8aa3b, v109

; DEV void gdn_sample_item(const Params& p, int item, unsigned char* lds) {
;     ...
;         gt[t] = __expf(-__expf(p.in[11][h]) * sp);
	v_exp_f32_e32 v72, v109


; DEV float silu_f(float x) { return x / (1.f + __expf(-x)); }
	v_add_f32_e32 v106, 1.0, v74


; DEV void gdn_sample_item(const Params& p, int item, unsigned char* lds) {
;     ...
;         bt[t] = 1.f / (1.f + __expf(-bb));
	v_rcp_f32_e32 v74, v112
	s_nop 0
	v_mul_f32_e32 v126, 1.0, v74


; DEV void gdn_sample_item(const Params& p, int item, unsigned char* lds) {
;     ...
;         const float* kk = ksh + t * 128 + half * 64; const float* qq = qsh + t * 128 + half * 64;
;         f32x2_t ks2 = {0.f, 0.f};
; #pragma unroll
;         for (int d4 = 0; d4 < 16; ++d4) { const f32x4 k4 = *(const f32x4*)(kk + d4 * 4); ks2 += (f32x2_t){k4[0], k4[1]} * S[d4 * 2]; ks2 += (f32x2_t){k4[2], k4[3]} * S[d4 * 2 + 1]; }
	ds_read_b128 v[74:77], v111 offset:1536
	ds_read_b128 v[112:115], v111 offset:1552
	ds_read_b128 v[116:119], v111 offset:1568
	ds_read_b128 v[120:123], v111 offset:1584


; DEV void gdn_sample_item(const Params& p, int item, unsigned char* lds) {
;     ...
;         for (int d4 = 0; d4 < 16; ++d4) { const f32x4 k4 = *(const f32x4*)(kk + d4 * 4); ks2 += (f32x2_t){k4[0], k4[1]} * S[d4 * 2]; ks2 += (f32x2_t){k4[2], k4[3]} * S[d4 * 2 + 1]; }
	s_waitcnt lgkmcnt(3)
	v_pk_fma_f32 v[74:75], v[10:11], v[74:75], 0 op_sel_hi:[1,1,0]

; DEV void gdn_sample_item(const Params& p, int item, unsigned char* lds) {
;     ...
;         for (int d4 = 0; d4 < 16; ++d4) { const f32x4 k4 = *(const f32x4*)(kk + d4 * 4); ks2 += (f32x2_t){k4[0], k4[1]} * S[d4 * 2]; ks2 += (f32x2_t){k4[2], k4[3]} * S[d4 * 2 + 1]; }
	v_pk_fma_f32 v[74:75], v[12:13], v[76:77], v[74:75]

; DEV void gdn_sample_item(const Params& p, int item, unsigned char* lds) {
;     ...
;         for (int d4 = 0; d4 < 16; ++d4) { const f32x4 k4 = *(const f32x4*)(kk + d4 * 4); ks2 += (f32x2_t){k4[0], k4[1]} * S[d4 * 2]; ks2 += (f32x2_t){k4[2], k4[3]} * S[d4 * 2 + 1]; }
	s_waitcnt lgkmcnt(2)
	v_pk_fma_f32 v[74:75], v[14:15], v[112:113], v[74:75]
	s_nop 0
	v_pk_fma_f32 v[74:75], v[16:17], v[114:115], v[74:75]
	ds_read_b128 v[112:115], v111 offset:1616
	s_waitcnt lgkmcnt(2)
	v_pk_fma_f32 v[108:109], v[18:19], v[116:117], v[74:75]
	ds_read_b128 v[74:77], v111 offset:1600
	v_pk_fma_f32 v[108:109], v[20:21], v[118:119], v[108:109]
	ds_read_b128 v[116:119], v111 offset:1632
	s_waitcnt lgkmcnt(3)
	v_pk_fma_f32 v[108:109], v[22:23], v[120:121], v[108:109]
	s_nop 0
	v_pk_fma_f32 v[108:109], v[24:25], v[122:123], v[108:109]
	s_waitcnt lgkmcnt(1)
	v_pk_fma_f32 v[74:75], v[26:27], v[74:75], v[108:109]
	s_nop 0
	v_pk_fma_f32 v[74:75], v[28:29], v[76:77], v[74:75]
	s_nop 0
	v_pk_fma_f32 v[108:109], v[30:31], v[112:113], v[74:75]
	ds_read_b128 v[74:77], v111 offset:1648
	v_pk_fma_f32 v[108:109], v[32:33], v[114:115], v[108:109]
	ds_read_b128 v[112:115], v111 offset:1664
	s_waitcnt lgkmcnt(2)
	v_pk_fma_f32 v[108:109], v[34:35], v[116:117], v[108:109]
	s_nop 0
	v_pk_fma_f32 v[108:109], v[36:37], v[118:119], v[108:109]
	ds_read_b128 v[116:119], v111 offset:1680
	s_waitcnt lgkmcnt(2)
	v_pk_fma_f32 v[74:75], v[38:39], v[74:75], v[108:109]
	s_nop 0
	v_pk_fma_f32 v[74:75], v[40:41], v[76:77], v[74:75]
	s_waitcnt lgkmcnt(1)
	v_pk_fma_f32 v[108:109], v[42:43], v[112:113], v[74:75]
	ds_read_b128 v[74:77], v111 offset:1696
	v_pk_fma_f32 v[108:109], v[44:45], v[114:115], v[108:109]
	ds_read_b128 v[112:115], v111 offset:1712
	s_waitcnt lgkmcnt(2)
	v_pk_fma_f32 v[108:109], v[46:47], v[116:117], v[108:109]
	s_nop 0
	v_pk_fma_f32 v[108:109], v[48:49], v[118:119], v[108:109]
	ds_read_b128 v[116:119], v111 offset:1728
	s_waitcnt lgkmcnt(2)
	v_pk_fma_f32 v[74:75], v[50:51], v[74:75], v[108:109]
	s_nop 0
	v_pk_fma_f32 v[74:75], v[52:53], v[76:77], v[74:75]
	s_waitcnt lgkmcnt(1)
	v_pk_fma_f32 v[74:75], v[54:55], v[112:113], v[74:75]
	s_nop 0
	v_pk_fma_f32 v[108:109], v[56:57], v[114:115], v[74:75]
	ds_read_b128 v[74:77], v111 offset:1744
	ds_read_b128 v[112:115], v111 offset:1760
	s_waitcnt lgkmcnt(2)
	v_pk_fma_f32 v[108:109], v[58:59], v[116:117], v[108:109]
	s_nop 0
	v_pk_fma_f32 v[108:109], v[60:61], v[118:119], v[108:109]
	ds_read_b128 v[116:119], v111 offset:1776
	s_waitcnt lgkmcnt(2)
	v_pk_fma_f32 v[74:75], v[62:63], v[74:75], v[108:109]
	s_nop 0
	v_pk_fma_f32 v[74:75], v[64:65], v[76:77], v[74:75]

; DEV void gdn_sample_item(const Params& p, int item, unsigned char* lds) {
;     ...
;         for (int d4 = 0; d4 < 16; ++d4) { const f32x4 k4 = *(const f32x4*)(kk + d4 * 4); ks2 += (f32x2_t){k4[0], k4[1]} * S[d4 * 2]; ks2 += (f32x2_t){k4[2], k4[3]} * S[d4 * 2 + 1]; }
	s_waitcnt lgkmcnt(1)
	v_pk_fma_f32 v[74:75], v[66:67], v[112:113], v[74:75]

; DEV void gdn_sample_item(const Params& p, int item, unsigned char* lds) {
;     ...
;         for (int d4 = 0; d4 < 16; ++d4) { const f32x4 k4 = *(const f32x4*)(kk + d4 * 4); ks2 += (f32x2_t){k4[0], k4[1]} * S[d4 * 2]; ks2 += (f32x2_t){k4[2], k4[3]} * S[d4 * 2 + 1]; }
;         part[(t * 2 + half) * 128 + c] = ks2[0] + ks2[1];
;         __syncthreads();
;         const float kS = part[(t * 2) * 128 + c] + part[(t * 2 + 1) * 128 + c];
;         const float eg = gt[t], dl = bt[t] * (vv[t] - eg * kS);
;         const f32x2_t eg2 = {eg, eg}, dl2 = {dl, dl};
;         f32x2_t o2 = {0.f, 0.f};
; #pragma unroll
;         for (int d4 = 0; d4 < 16; ++d4) {
;             const f32x4 k4 = *(const f32x4*)(kk + d4 * 4), q4 = *(const f32x4*)(qq + d4 * 4);
;             const f32x2_t s0 = S[d4 * 2] * eg2 + (f32x2_t){k4[0], k4[1]} * dl2, s1 = S[d4 * 2 + 1] * eg2 + (f32x2_t){k4[2], k4[3]} * dl2;
;             S[d4 * 2] = s0; S[d4 * 2 + 1] = s1;
;             o2 += (f32x2_t){q4[0], q4[1]} * s0; o2 += (f32x2_t){q4[2], q4[3]} * s1;
;         }
	v_pk_fma_f32 v[74:75], v[68:69], v[114:115], v[74:75]
	v_rcp_f32_e32 v76, v106
	s_nop 0
	v_mul_f32_e32 v76, v110, v76
	s_waitcnt lgkmcnt(0)
	v_pk_fma_f32 v[74:75], v[70:71], v[116:117], v[74:75]
	s_nop 0
	v_pk_fma_f32 v[74:75], v[8:9], v[118:119], v[74:75]
	s_nop 0
	v_add_f32_e32 v74, v74, v75
	ds_write_b32 v105, v74 offset:7424
	s_waitcnt lgkmcnt(0)
	s_barrier
	ds_read2st64_b32 v[74:75], v131 offset0:29 offset1:31
	s_waitcnt lgkmcnt(0)
	v_add_f32_e32 v74, v74, v75
	v_fma_f32 v74, -v72, v74, v76
	v_mul_f32_e32 v106, v126, v74
	ds_read_b128 v[74:77], v111 offset:1536
	ds_read_b128 v[112:115], v111 offset:1552
	ds_read_b128 v[116:119], v111 offset:1568
	ds_read_b128 v[120:123], v111 offset:1584
	ds_read_b128 v[124:127], v111 offset:3584
	s_waitcnt lgkmcnt(4)
	v_pk_mul_f32 v[74:75], v[74:75], v[106:107] op_sel_hi:[1,0]
	ds_read_b128 v[128:131], v111 offset:3600
	v_pk_fma_f32 v[10:11], v[72:73], v[10:11], v[74:75] op_sel_hi:[0,1,1]
	v_pk_mul_f32 v[74:75], v[76:77], v[106:107] op_sel_hi:[1,0]
	s_nop 0
	v_pk_fma_f32 v[12:13], v[72:73], v[12:13], v[74:75] op_sel_hi:[0,1,1]
	s_waitcnt lgkmcnt(1)
	v_pk_fma_f32 v[74:75], v[124:125], v[10:11], 0 op_sel_hi:[1,1,0]
	s_nop 0
	v_pk_fma_f32 v[108:109], v[126:127], v[12:13], v[74:75]
	v_pk_mul_f32 v[74:75], v[112:113], v[106:107] op_sel_hi:[1,0]
	s_nop 0
	v_pk_fma_f32 v[74:75], v[72:73], v[14:15], v[74:75] op_sel_hi:[0,1,1]
	v_pk_mul_f32 v[14:15], v[114:115], v[106:107] op_sel_hi:[1,0]
	ds_read_b128 v[112:115], v111 offset:3616
	v_pk_fma_f32 v[76:77], v[72:73], v[16:17], v[14:15] op_sel_hi:[0,1,1]
	s_waitcnt lgkmcnt(1)
	v_pk_fma_f32 v[14:15], v[128:129], v[74:75], v[108:109]
	v_pk_mul_f32 v[16:17], v[106:107], v[118:119] op_sel_hi:[0,1]
	v_pk_fma_f32 v[108:109], v[130:131], v[76:77], v[14:15]
	v_pk_mul_f32 v[14:15], v[106:107], v[116:117] op_sel_hi:[0,1]
	v_pk_fma_f32 v[14:15], v[72:73], v[18:19], v[14:15] op_sel_hi:[0,1,1]
	ds_read_b128 v[116:119], v111 offset:3632
	v_pk_fma_f32 v[16:17], v[72:73], v[20:21], v[16:17] op_sel_hi:[0,1,1]
	s_waitcnt lgkmcnt(1)
	v_pk_fma_f32 v[18:19], v[112:113], v[14:15], v[108:109]
	v_pk_mul_f32 v[20:21], v[106:107], v[122:123] op_sel_hi:[0,1]
	v_pk_fma_f32 v[108:109], v[114:115], v[16:17], v[18:19]
	v_pk_mul_f32 v[18:19], v[106:107], v[120:121] op_sel_hi:[0,1]
	v_pk_fma_f32 v[18:19], v[72:73], v[22:23], v[18:19] op_sel_hi:[0,1,1]
	v_pk_fma_f32 v[20:21], v[72:73], v[24:25], v[20:21] op_sel_hi:[0,1,1]
	ds_read_b128 v[22:25], v111 offset:1600
	s_waitcnt lgkmcnt(1)
	v_pk_fma_f32 v[108:109], v[116:117], v[18:19], v[108:109]
	s_waitcnt lgkmcnt(0)
	v_pk_mul_f32 v[22:23], v[106:107], v[22:23] op_sel_hi:[0,1]
	v_pk_fma_f32 v[108:109], v[118:119], v[20:21], v[108:109]
	ds_read_b128 v[112:115], v111 offset:3648
	ds_read_b128 v[116:119], v111 offset:1616
	v_pk_fma_f32 v[22:23], v[72:73], v[26:27], v[22:23] op_sel_hi:[0,1,1]
	v_pk_mul_f32 v[24:25], v[106:107], v[24:25] op_sel_hi:[0,1]
	v_pk_fma_f32 v[24:25], v[72:73], v[28:29], v[24:25] op_sel_hi:[0,1,1]
	s_waitcnt lgkmcnt(1)
	v_pk_fma_f32 v[26:27], v[112:113], v[22:23], v[108:109]
	s_waitcnt lgkmcnt(0)
	v_pk_mul_f32 v[28:29], v[106:107], v[118:119] op_sel_hi:[0,1]
	v_pk_fma_f32 v[108:109], v[114:115], v[24:25], v[26:27]
	v_pk_mul_f32 v[26:27], v[106:107], v[116:117] op_sel_hi:[0,1]
	ds_read_b128 v[120:123], v111 offset:3664
	v_pk_fma_f32 v[26:27], v[72:73], v[30:31], v[26:27] op_sel_hi:[0,1,1]
	v_pk_fma_f32 v[28:29], v[72:73], v[32:33], v[28:29] op_sel_hi:[0,1,1]
	ds_read_b128 v[30:33], v111 offset:1632
	ds_read_b128 v[112:115], v111 offset:3680
	ds_read_b128 v[116:119], v111 offset:1648
	s_waitcnt lgkmcnt(3)
	v_pk_fma_f32 v[108:109], v[120:121], v[26:27], v[108:109]
	s_waitcnt lgkmcnt(2)
	v_pk_mul_f32 v[30:31], v[106:107], v[30:31] op_sel_hi:[0,1]
	v_pk_fma_f32 v[108:109], v[122:123], v[28:29], v[108:109]
	v_pk_fma_f32 v[30:31], v[72:73], v[34:35], v[30:31] op_sel_hi:[0,1,1]
	v_pk_mul_f32 v[32:33], v[106:107], v[32:33] op_sel_hi:[0,1]
	v_pk_fma_f32 v[32:33], v[72:73], v[36:37], v[32:33] op_sel_hi:[0,1,1]
	s_waitcnt lgkmcnt(1)
	v_pk_fma_f32 v[34:35], v[112:113], v[30:31], v[108:109]
	s_waitcnt lgkmcnt(0)
	v_pk_mul_f32 v[36:37], v[106:107], v[118:119] op_sel_hi:[0,1]
	v_pk_fma_f32 v[108:109], v[114:115], v[32:33], v[34:35]
	v_pk_mul_f32 v[34:35], v[106:107], v[116:117] op_sel_hi:[0,1]
	ds_read_b128 v[120:123], v111 offset:3696
	v_pk_fma_f32 v[34:35], v[72:73], v[38:39], v[34:35] op_sel_hi:[0,1,1]
	v_pk_fma_f32 v[36:37], v[72:73], v[40:41], v[36:37] op_sel_hi:[0,1,1]
	ds_read_b128 v[38:41], v111 offset:1664
	ds_read_b128 v[112:115], v111 offset:3712
	ds_read_b128 v[116:119], v111 offset:1680
	s_waitcnt lgkmcnt(3)
	v_pk_fma_f32 v[108:109], v[120:121], v[34:35], v[108:109]
	s_waitcnt lgkmcnt(2)
	v_pk_mul_f32 v[38:39], v[106:107], v[38:39] op_sel_hi:[0,1]
	v_pk_fma_f32 v[108:109], v[122:123], v[36:37], v[108:109]
	v_pk_fma_f32 v[38:39], v[72:73], v[42:43], v[38:39] op_sel_hi:[0,1,1]
	v_pk_mul_f32 v[40:41], v[106:107], v[40:41] op_sel_hi:[0,1]
	v_pk_fma_f32 v[40:41], v[72:73], v[44:45], v[40:41] op_sel_hi:[0,1,1]
	s_waitcnt lgkmcnt(1)
	v_pk_fma_f32 v[42:43], v[112:113], v[38:39], v[108:109]
	s_waitcnt lgkmcnt(0)
	v_pk_mul_f32 v[44:45], v[106:107], v[118:119] op_sel_hi:[0,1]
	v_pk_fma_f32 v[108:109], v[114:115], v[40:41], v[42:43]
	v_pk_mul_f32 v[42:43], v[106:107], v[116:117] op_sel_hi:[0,1]
	ds_read_b128 v[120:123], v111 offset:3728
	v_pk_fma_f32 v[42:43], v[72:73], v[46:47], v[42:43] op_sel_hi:[0,1,1]
	v_pk_fma_f32 v[44:45], v[72:73], v[48:49], v[44:45] op_sel_hi:[0,1,1]
	ds_read_b128 v[46:49], v111 offset:1696
	ds_read_b128 v[112:115], v111 offset:3744
	ds_read_b128 v[116:119], v111 offset:1712
	s_waitcnt lgkmcnt(3)
; DEV void gdn_sample_item(const Params& p, int item, unsigned char* lds) {
;     ...
;         for (int d4 = 0; d4 < 16; ++d4) {
;             const f32x4 k4 = *(const f32x4*)(kk + d4 * 4), q4 = *(const f32x4*)(qq + d4 * 4);
;             const f32x2_t s0 = S[d4 * 2] * eg2 + (f32x2_t){k4[0], k4[1]} * dl2, s1 = S[d4 * 2 + 1] * eg2 + (f32x2_t){k4[2], k4[3]} * dl2;
;             S[d4 * 2] = s0; S[d4 * 2 + 1] = s1;
;             o2 += (f32x2_t){q4[0], q4[1]} * s0; o2 += (f32x2_t){q4[2], q4[3]} * s1;
;         }
;         const float o = o2[0] + o2[1];
;         ot[t] = o;
;         if (half == 1) opart[t * 128 + c] = o;
;     }
;     float* dso = p.out + O_DS + ((size_t)(sb * 8 + h) * 128 + half * 64) * 128 + c;
; #pragma unroll
;     for (int d = 0; d < 64; ++d) __builtin_nontemporal_store(S[d >> 1][d & 1], dso + (size_t)d * 128);
	v_pk_fma_f32 v[108:109], v[120:121], v[42:43], v[108:109]
	s_waitcnt lgkmcnt(2)
	v_pk_mul_f32 v[46:47], v[106:107], v[46:47] op_sel_hi:[0,1]
	v_pk_fma_f32 v[108:109], v[122:123], v[44:45], v[108:109]
	v_pk_fma_f32 v[46:47], v[72:73], v[50:51], v[46:47] op_sel_hi:[0,1,1]
	v_pk_mul_f32 v[48:49], v[106:107], v[48:49] op_sel_hi:[0,1]
	v_pk_fma_f32 v[48:49], v[72:73], v[52:53], v[48:49] op_sel_hi:[0,1,1]
	s_waitcnt lgkmcnt(1)
	v_pk_fma_f32 v[50:51], v[112:113], v[46:47], v[108:109]
	s_waitcnt lgkmcnt(0)
	v_pk_mul_f32 v[52:53], v[106:107], v[118:119] op_sel_hi:[0,1]
	v_pk_fma_f32 v[108:109], v[114:115], v[48:49], v[50:51]
	v_pk_mul_f32 v[50:51], v[106:107], v[116:117] op_sel_hi:[0,1]
	ds_read_b128 v[120:123], v111 offset:3760
	v_pk_fma_f32 v[50:51], v[72:73], v[54:55], v[50:51] op_sel_hi:[0,1,1]
	v_pk_fma_f32 v[52:53], v[72:73], v[56:57], v[52:53] op_sel_hi:[0,1,1]
	ds_read_b128 v[54:57], v111 offset:1728
	ds_read_b128 v[112:115], v111 offset:3776
	ds_read_b128 v[116:119], v111 offset:1744
	s_waitcnt lgkmcnt(3)
	v_pk_fma_f32 v[108:109], v[120:121], v[50:51], v[108:109]
	s_waitcnt lgkmcnt(2)
	v_pk_mul_f32 v[54:55], v[106:107], v[54:55] op_sel_hi:[0,1]
	v_pk_fma_f32 v[108:109], v[122:123], v[52:53], v[108:109]
	v_pk_fma_f32 v[54:55], v[72:73], v[58:59], v[54:55] op_sel_hi:[0,1,1]
	v_pk_mul_f32 v[56:57], v[106:107], v[56:57] op_sel_hi:[0,1]
	v_pk_fma_f32 v[56:57], v[72:73], v[60:61], v[56:57] op_sel_hi:[0,1,1]
	s_waitcnt lgkmcnt(1)
	v_pk_fma_f32 v[58:59], v[112:113], v[54:55], v[108:109]
	ds_read_b128 v[120:123], v111 offset:3792
	v_pk_fma_f32 v[108:109], v[114:115], v[56:57], v[58:59]
	s_waitcnt lgkmcnt(1)
	v_pk_mul_f32 v[58:59], v[106:107], v[116:117] op_sel_hi:[0,1]
	v_pk_mul_f32 v[60:61], v[106:107], v[118:119] op_sel_hi:[0,1]
	v_pk_fma_f32 v[58:59], v[72:73], v[62:63], v[58:59] op_sel_hi:[0,1,1]
	v_pk_fma_f32 v[60:61], v[72:73], v[64:65], v[60:61] op_sel_hi:[0,1,1]
	ds_read_b128 v[62:65], v111 offset:1760
	ds_read_b128 v[112:115], v111 offset:3808
	ds_read_b128 v[116:119], v111 offset:1776
	s_waitcnt lgkmcnt(3)
	v_pk_fma_f32 v[108:109], v[120:121], v[58:59], v[108:109]
	s_waitcnt lgkmcnt(2)
	v_pk_mul_f32 v[62:63], v[106:107], v[62:63] op_sel_hi:[0,1]
	v_pk_fma_f32 v[120:121], v[122:123], v[60:61], v[108:109]
	ds_read_b128 v[108:111], v111 offset:3824
	v_pk_fma_f32 v[62:63], v[72:73], v[66:67], v[62:63] op_sel_hi:[0,1,1]
	v_pk_mul_f32 v[64:65], v[106:107], v[64:65] op_sel_hi:[0,1]
	v_pk_fma_f32 v[64:65], v[72:73], v[68:69], v[64:65] op_sel_hi:[0,1,1]
	s_waitcnt lgkmcnt(2)
	v_pk_fma_f32 v[66:67], v[112:113], v[62:63], v[120:121]
	s_nop 0
	v_pk_fma_f32 v[68:69], v[114:115], v[64:65], v[66:67]
	s_waitcnt lgkmcnt(1)
	v_pk_mul_f32 v[66:67], v[106:107], v[116:117] op_sel_hi:[0,1]
	v_pk_fma_f32 v[66:67], v[72:73], v[70:71], v[66:67] op_sel_hi:[0,1,1]
	v_pk_mul_f32 v[70:71], v[106:107], v[118:119] op_sel_hi:[0,1]
	v_pk_fma_f32 v[8:9], v[72:73], v[8:9], v[70:71] op_sel_hi:[0,1,1]
	s_waitcnt lgkmcnt(0)
	v_pk_fma_f32 v[68:69], v[108:109], v[66:67], v[68:69]
	s_nop 0
	v_pk_fma_f32 v[68:69], v[110:111], v[8:9], v[68:69]
	s_nop 0
	v_add_f32_e32 v68, v68, v69
	s_and_saveexec_b64 s[52:53], s[8:9]
	v_lshl_or_b32 v69, v97, 2, v94
	v_add_u32_e32 v69, s70, v69
	ds_write_b32 v69, v68 offset:8448
	s_or_b64 exec, exec, s[52:53]
	v_lshl_add_u64 v[6:7], v[6:7], 2, s[12:13]
	v_lshl_add_u64 v[6:7], v[6:7], 0, v[2:3]
	global_store_dword v[6:7], v10, off nt
	global_store_dword v[6:7], v11, off offset:512 nt
	global_store_dword v[6:7], v12, off offset:1024 nt
	global_store_dword v[6:7], v13, off offset:1536 nt
	global_store_dword v[6:7], v74, off offset:2048 nt
	global_store_dword v[6:7], v75, off offset:2560 nt
	global_store_dword v[6:7], v76, off offset:3072 nt
	global_store_dword v[6:7], v77, off offset:3584 nt
	v_add_co_u32_e32 v10, vcc, s85, v6
	s_nop 1
	v_addc_co_u32_e32 v11, vcc, 0, v7, vcc
	v_add_co_u32_e32 v12, vcc, s65, v6
	s_nop 1
	v_addc_co_u32_e32 v13, vcc, 0, v7, vcc
	global_store_dword v[12:13], v14, off offset:-4096 nt
	global_store_dword v[10:11], v15, off offset:512 nt
	global_store_dword v[10:11], v16, off offset:1024 nt
	global_store_dword v[10:11], v17, off offset:1536 nt
	global_store_dword v[10:11], v18, off offset:2048 nt
	global_store_dword v[10:11], v19, off offset:2560 nt
	global_store_dword v[10:11], v20, off offset:3072 nt
	global_store_dword v[10:11], v21, off offset:3584 nt
	global_store_dword v[12:13], v22, off nt
	global_store_dword v[12:13], v23, off offset:512 nt
	global_store_dword v[12:13], v24, off offset:1024 nt
	global_store_dword v[12:13], v25, off offset:1536 nt
	global_store_dword v[12:13], v26, off offset:2048 nt
	global_store_dword v[12:13], v27, off offset:2560 nt
	global_store_dword v[12:13], v28, off offset:3072 nt
	global_store_dword v[12:13], v29, off offset:3584 nt
	v_add_co_u32_e32 v10, vcc, s66, v6
	s_nop 1
	v_addc_co_u32_e32 v11, vcc, 0, v7, vcc
	v_add_co_u32_e32 v12, vcc, s68, v6
	s_nop 1
	v_addc_co_u32_e32 v13, vcc, 0, v7, vcc
	global_store_dword v[12:13], v30, off offset:-4096 nt
	global_store_dword v[10:11], v31, off offset:512 nt
	global_store_dword v[10:11], v32, off offset:1024 nt
	global_store_dword v[10:11], v33, off offset:1536 nt
	global_store_dword v[10:11], v34, off offset:2048 nt
	global_store_dword v[10:11], v35, off offset:2560 nt
	global_store_dword v[10:11], v36, off offset:3072 nt
	global_store_dword v[10:11], v37, off offset:3584 nt
	global_store_dword v[12:13], v38, off nt
	global_store_dword v[12:13], v39, off offset:512 nt
	global_store_dword v[12:13], v40, off offset:1024 nt
	global_store_dword v[12:13], v41, off offset:1536 nt
	global_store_dword v[12:13], v42, off offset:2048 nt
; DEV float wave_sum(float v) {
; #pragma unroll
;     for (int o = 32; o >= 1; o >>= 1) v += __shfl_xor(v, o);
;     return v;
; DEV void gdn_sample_item(const Params& p, int item, unsigned char* lds) {
;     ...
;     for (int d = 0; d < 64; ++d) __builtin_nontemporal_store(S[d >> 1][d & 1], dso + (size_t)d * 128);
;     __syncthreads();
;     if (half == 0) {
; #pragma unroll
;         for (int t = 0; t < 4; ++t) { ot[t] += opart[t * 128 + c]; const float a = wave_sum(ot[t] * ot[t]); if (lane == 0) red2[wid * 4 + t] = a; }
;     }
	global_store_dword v[12:13], v43, off offset:2560 nt
	global_store_dword v[12:13], v44, off offset:3072 nt
	global_store_dword v[12:13], v45, off offset:3584 nt
	v_add_co_u32_e32 v10, vcc, s74, v6
	s_nop 1
	v_addc_co_u32_e32 v11, vcc, 0, v7, vcc
	v_add_co_u32_e32 v12, vcc, s67, v6
	s_nop 1
	v_addc_co_u32_e32 v13, vcc, 0, v7, vcc
	v_add_co_u32_e32 v6, vcc, s69, v6
	global_store_dword v[12:13], v46, off offset:-4096 nt
	global_store_dword v[10:11], v47, off offset:512 nt
	global_store_dword v[10:11], v48, off offset:1024 nt
	global_store_dword v[10:11], v49, off offset:1536 nt
	global_store_dword v[10:11], v50, off offset:2048 nt
	global_store_dword v[10:11], v51, off offset:2560 nt
	global_store_dword v[10:11], v52, off offset:3072 nt
	global_store_dword v[10:11], v53, off offset:3584 nt
	global_store_dword v[12:13], v54, off nt
	global_store_dword v[12:13], v55, off offset:512 nt
	global_store_dword v[12:13], v56, off offset:1024 nt
	global_store_dword v[12:13], v57, off offset:1536 nt
	global_store_dword v[12:13], v58, off offset:2048 nt
	global_store_dword v[12:13], v59, off offset:2560 nt
	global_store_dword v[12:13], v60, off offset:3072 nt
	global_store_dword v[12:13], v61, off offset:3584 nt
	v_addc_co_u32_e32 v7, vcc, 0, v7, vcc
	global_store_dword v[6:7], v62, off nt
	global_store_dword v[6:7], v63, off offset:512 nt
	global_store_dword v[6:7], v64, off offset:1024 nt
	global_store_dword v[6:7], v65, off offset:1536 nt
	global_store_dword v[6:7], v66, off offset:2048 nt
	global_store_dword v[6:7], v67, off offset:2560 nt
	global_store_dword v[6:7], v8, off offset:3072 nt
	global_store_dword v[6:7], v9, off offset:3584 nt
	s_waitcnt lgkmcnt(0)
	s_barrier
	s_and_saveexec_b64 s[8:9], s[6:7]
	s_cbranch_execz .LBB0_866
	ds_read_b32 v6, v105 offset:8448
	s_waitcnt lgkmcnt(0)
	v_add_f32_e32 v5, v5, v6
	v_mul_f32_e32 v6, v5, v5
	v_mov_b32_e32 v178, v6
	v_mov_b32_e32 v179, v6
	s_nop 1
	v_permlane32_swap_b32_e32 v178, v179
	v_cndmask_b32_e64 v6, v178, v179, s[90:91]
	s_waitcnt lgkmcnt(0)
	v_fmac_f32_e32 v6, v5, v5
	v_mov_b32_e32 v178, v6
	v_mov_b32_e32 v179, v6
	s_nop 1
	v_permlane16_swap_b32_e32 v178, v179
	v_cndmask_b32_e64 v7, v178, v179, s[92:93]
	s_waitcnt lgkmcnt(0)
	v_add_f32_e32 v6, v6, v7
	s_nop 1
	v_mov_b32_dpp v7, v6 row_ror:8 row_mask:0xf bank_mask:0xf
	s_waitcnt lgkmcnt(0)
	v_add_f32_e32 v6, v6, v7
	s_nop 1
	v_mov_b32_dpp v178, v6 row_shr:4 row_mask:0xf bank_mask:0xa
	s_nop 0
	v_mov_b32_dpp v178, v6 row_shl:4 row_mask:0xf bank_mask:0x5
	v_mov_b32_e32 v7, v178
	s_waitcnt lgkmcnt(0)
	v_add_f32_e32 v6, v6, v7
	s_nop 1
	v_mov_b32_dpp v7, v6 quad_perm:[2,3,0,1] row_mask:0xf bank_mask:0xf
	s_waitcnt lgkmcnt(0)
	v_add_f32_e32 v7, v6, v7
	s_nop 1
	v_mov_b32_dpp v8, v7 quad_perm:[1,0,3,2] row_mask:0xf bank_mask:0xf
	v_lshlrev_b32_e32 v6, 2, v104
	v_lshl_add_u32 v6, v6, 2, s70
	s_and_saveexec_b64 s[52:53], s[4:5]
	s_cbranch_execz .LBB0_859
	s_waitcnt lgkmcnt(0)
	v_add_f32_e32 v7, v7, v8
	ds_write_b32 v6, v7 offset:4224
.LBB0_859:
	s_or_b64 exec, exec, s[52:53]
	ds_read_b32 v7, v105 offset:8960
	s_waitcnt lgkmcnt(0)
	v_add_f32_e32 v73, v73, v7
	v_mul_f32_e32 v7, v73, v73
	v_mov_b32_e32 v178, v7
	v_mov_b32_e32 v179, v7
	s_nop 1
	v_permlane32_swap_b32_e32 v178, v179
	v_cndmask_b32_e64 v7, v178, v179, s[90:91]
	s_waitcnt lgkmcnt(0)
	v_fmac_f32_e32 v7, v73, v73
	v_mov_b32_e32 v178, v7
	v_mov_b32_e32 v179, v7
	s_nop 1
	v_permlane16_swap_b32_e32 v178, v179
	v_cndmask_b32_e64 v8, v178, v179, s[92:93]
	s_waitcnt lgkmcnt(0)
	v_add_f32_e32 v7, v7, v8
	s_nop 1
	v_mov_b32_dpp v8, v7 row_ror:8 row_mask:0xf bank_mask:0xf
	s_waitcnt lgkmcnt(0)
	v_add_f32_e32 v7, v7, v8
	s_nop 1
	v_mov_b32_dpp v178, v7 row_shr:4 row_mask:0xf bank_mask:0xa
	s_nop 0
	v_mov_b32_dpp v178, v7 row_shl:4 row_mask:0xf bank_mask:0x5
	v_mov_b32_e32 v8, v178
	s_waitcnt lgkmcnt(0)
	v_add_f32_e32 v7, v7, v8
	s_nop 1
	v_mov_b32_dpp v8, v7 quad_perm:[2,3,0,1] row_mask:0xf bank_mask:0xf
	s_waitcnt lgkmcnt(0)
	v_add_f32_e32 v7, v7, v8
	s_nop 1
	v_mov_b32_dpp v8, v7 quad_perm:[1,0,3,2] row_mask:0xf bank_mask:0xf
	s_and_saveexec_b64 s[52:53], s[4:5]
	s_cbranch_execz .LBB0_861
	s_waitcnt lgkmcnt(0)
	v_add_f32_e32 v7, v7, v8
	ds_write_b32 v6, v7 offset:4228
.LBB0_861:
	s_or_b64 exec, exec, s[52:53]
	ds_read_b32 v7, v105 offset:9472
	s_waitcnt lgkmcnt(0)
	v_add_f32_e32 v107, v107, v7
	v_mul_f32_e32 v7, v107, v107
	v_mov_b32_e32 v178, v7
	v_mov_b32_e32 v179, v7
	s_nop 1
	v_permlane32_swap_b32_e32 v178, v179
	v_cndmask_b32_e64 v7, v178, v179, s[90:91]
	s_waitcnt lgkmcnt(0)
	v_fmac_f32_e32 v7, v107, v107
	v_mov_b32_e32 v178, v7
	v_mov_b32_e32 v179, v7
	s_nop 1
	v_permlane16_swap_b32_e32 v178, v179
	v_cndmask_b32_e64 v8, v178, v179, s[92:93]
	s_waitcnt lgkmcnt(0)
	v_add_f32_e32 v7, v7, v8
	s_nop 1
	v_mov_b32_dpp v8, v7 row_ror:8 row_mask:0xf bank_mask:0xf
	s_waitcnt lgkmcnt(0)
	v_add_f32_e32 v7, v7, v8
	s_nop 1
	v_mov_b32_dpp v178, v7 row_shr:4 row_mask:0xf bank_mask:0xa
	s_nop 0
	v_mov_b32_dpp v178, v7 row_shl:4 row_mask:0xf bank_mask:0x5
	v_mov_b32_e32 v8, v178
	s_waitcnt lgkmcnt(0)
	v_add_f32_e32 v7, v7, v8
	s_nop 1
	v_mov_b32_dpp v8, v7 quad_perm:[2,3,0,1] row_mask:0xf bank_mask:0xf
	s_waitcnt lgkmcnt(0)
	v_add_f32_e32 v7, v7, v8
	s_nop 1
	v_mov_b32_dpp v8, v7 quad_perm:[1,0,3,2] row_mask:0xf bank_mask:0xf
	s_and_saveexec_b64 s[52:53], s[4:5]
	s_cbranch_execz .LBB0_863
	s_waitcnt lgkmcnt(0)
	v_add_f32_e32 v7, v7, v8
	ds_write_b32 v6, v7 offset:4232
.LBB0_863:
	s_or_b64 exec, exec, s[52:53]
	ds_read_b32 v7, v105 offset:9984
	s_waitcnt lgkmcnt(0)
	v_add_f32_e32 v68, v68, v7
	v_mul_f32_e32 v7, v68, v68
	v_mov_b32_e32 v178, v7
	v_mov_b32_e32 v179, v7
	s_nop 1
	v_permlane32_swap_b32_e32 v178, v179
	v_cndmask_b32_e64 v7, v178, v179, s[90:91]
	s_waitcnt lgkmcnt(0)
	v_fmac_f32_e32 v7, v68, v68
	v_mov_b32_e32 v178, v7
	v_mov_b32_e32 v179, v7
	s_nop 1
	v_permlane16_swap_b32_e32 v178, v179
	v_cndmask_b32_e64 v8, v178, v179, s[92:93]
	s_waitcnt lgkmcnt(0)
	v_add_f32_e32 v7, v7, v8
	s_nop 1
	v_mov_b32_dpp v8, v7 row_ror:8 row_mask:0xf bank_mask:0xf
	s_waitcnt lgkmcnt(0)
	v_add_f32_e32 v7, v7, v8
	s_nop 1
	v_mov_b32_dpp v178, v7 row_shr:4 row_mask:0xf bank_mask:0xa
	s_nop 0
	v_mov_b32_dpp v178, v7 row_shl:4 row_mask:0xf bank_mask:0x5
	v_mov_b32_e32 v8, v178
	s_waitcnt lgkmcnt(0)
	v_add_f32_e32 v7, v7, v8
	s_nop 1
	v_mov_b32_dpp v8, v7 quad_perm:[2,3,0,1] row_mask:0xf bank_mask:0xf
	s_waitcnt lgkmcnt(0)
	v_add_f32_e32 v7, v7, v8
	s_nop 1
	v_mov_b32_dpp v8, v7 quad_perm:[1,0,3,2] row_mask:0xf bank_mask:0xf
	s_and_saveexec_b64 s[52:53], s[4:5]
	s_cbranch_execz .LBB0_865
	s_waitcnt lgkmcnt(0)
	v_add_f32_e32 v7, v7, v8
	ds_write_b32 v6, v7 offset:4236
